# stack: LN with earlier next-row loads and plain f32 ops + own-block prefetch + packed-op split incl. all of SWA + SWA counted wait
# speedup vs baseline: 1.0019x; 1.0019x over previous
; #define LAS __attribute__((address_space(3)))
; template <int MASK> ...
;     ...
;     for (int d0 = 0; d0 < 4; ++d0) {
;         const bf16x8 a0 = *(LAS const bf16x8*)(kp + d0 * 32), a1 = *(LAS const bf16x8*)(kp + 32 * 144 + d0 * 32);
;         p0 = __builtin_amdgcn_mfma_f32_32x32x16_bf16(a0, qf[d0], p0, 0, 0, 0);
;         p1 = __builtin_amdgcn_mfma_f32_32x32x16_bf16(a1, qf[d0], p1, 0, 0, 0);
;     }
;     constexpr float C2 = 0.125f * LOG2E;
;     const float NEG = -INFINITY;
;     if (MASK != 0) {
;         const int dk0 = kq + 4 * hi;
; #pragma unroll
;         for (int r = 0; r < 16; ++r) { const int kk = (r & 3) + 8 * (r >> 2);
;             if (MASK == 1) { if (dk0 > -kk) p0[r] = NEG; if (dk0 > -(kk + 32)) p1[r] = NEG; }
;             if (MASK == 3) { if (dk0 <= -128 - kk) p0[r] = NEG; if (dk0 <= -160 - kk) p1[r] = NEG; } }
;     }
;     float mr = fmaxf(p0[0], p1[0]);
; #pragma unroll
;     for (int r = 1; r < 16; ++r) mr = fmaxf(fmaxf(mr, p0[r]), p1[r]);
;     float mx = fmaf(mr, C2, off);
;     mx = fmaxf(mx, __shfl_xor(mx, 32));
;     const float mn = fmaxf(m, mx);
;     if (__ballot(mn > m) != 0ull) {
;         const float alpha = __builtin_amdgcn_exp2f(m - mn); l *= alpha;
; #pragma unroll
;         for (int r = 0; r < 16; ++r) { o0[r] *= alpha; o1[r] *= alpha; }
;     }
;     m = mn;
.LBB0_403:
	ds_read_b128 v[138:141], v129 offset:18432
	v_mfma_f32_32x32x16_bf16 v[32:47], v[92:95], v[64:67], 0
	v_readlane_b32 s0, v254, 18
	v_readlane_b32 s1, v254, 19
	s_waitcnt lgkmcnt(0)
	v_mfma_f32_32x32x16_bf16 v[32:47], v[138:141], v[112:115], v[32:47]
	ds_read_b128 v[138:141], v129 offset:23040
	v_mfma_f32_32x32x16_bf16 v[48:63], v[96:99], v[64:67], 0
	v_mul_f32_e32 v64, v134, v128
	s_waitcnt lgkmcnt(0)
	v_mfma_f32_32x32x16_bf16 v[48:63], v[138:141], v[112:115], v[48:63]
	ds_read_b128 v[112:115], v129 offset:18464
	s_waitcnt lgkmcnt(0)
	v_mfma_f32_32x32x16_bf16 v[32:47], v[112:115], v[108:111], v[32:47]
	ds_read_b128 v[112:115], v129 offset:23072
	s_waitcnt lgkmcnt(0)
	v_mfma_f32_32x32x16_bf16 v[48:63], v[112:115], v[108:111], v[48:63]
	ds_read_b128 v[108:111], v129 offset:18496
	s_waitcnt lgkmcnt(0)
	v_mfma_f32_32x32x16_bf16 v[32:47], v[108:111], v[104:107], v[32:47]
	ds_read_b128 v[108:111], v129 offset:23104
	s_waitcnt lgkmcnt(0)
	v_mfma_f32_32x32x16_bf16 v[48:63], v[108:111], v[104:107], v[48:63]
	ds_read_b128 v[104:107], v129 offset:18528
	s_waitcnt lgkmcnt(0)
	v_mfma_f32_32x32x16_bf16 v[32:47], v[104:107], v[100:103], v[32:47]
	ds_read_b128 v[104:107], v129 offset:23136
	s_waitcnt lgkmcnt(0)
	v_mfma_f32_32x32x16_bf16 v[48:63], v[104:107], v[100:103], v[48:63]
	s_nop 8
	v_cndmask_b32_e64 v110, v228, v32, s[0:1]
	v_readlane_b32 s0, v254, 20
	v_readlane_b32 s1, v254, 21
	v_cndmask_b32_e64 v32, v228, v63, s[70:71]
	s_nop 0
	v_cndmask_b32_e64 v111, v228, v48, s[0:1]
	v_readlane_b32 s0, v254, 22
	v_readlane_b32 s1, v254, 23
	s_nop 1
	v_cndmask_b32_e64 v108, v228, v33, s[0:1]
	v_readlane_b32 s0, v254, 24
	v_readlane_b32 s1, v254, 25
	v_cndmask_b32_e64 v33, v228, v47, s[52:53]
	s_nop 0
	v_cndmask_b32_e64 v109, v228, v49, s[0:1]
	v_readlane_b32 s0, v254, 26
	v_readlane_b32 s1, v254, 27
	s_nop 1
	v_cndmask_b32_e64 v106, v228, v34, s[0:1]
	v_readlane_b32 s0, v254, 28
	v_readlane_b32 s1, v254, 29
	s_nop 1
	v_cndmask_b32_e64 v107, v228, v50, s[0:1]
	v_readlane_b32 s0, v254, 30
	v_readlane_b32 s1, v254, 31
	s_nop 1
	v_cndmask_b32_e64 v104, v228, v35, s[0:1]
	v_readlane_b32 s0, v254, 32
	v_readlane_b32 s1, v254, 33
	s_nop 1
	v_cndmask_b32_e64 v105, v228, v51, s[0:1]
	v_readlane_b32 s0, v254, 34
	v_readlane_b32 s1, v254, 35
	s_nop 1
	v_cndmask_b32_e64 v102, v228, v36, s[0:1]
	v_readlane_b32 s0, v254, 36
	v_readlane_b32 s1, v254, 37
	s_nop 1
	v_cndmask_b32_e64 v103, v228, v52, s[0:1]
	v_readlane_b32 s0, v254, 38
	v_readlane_b32 s1, v254, 39
	s_nop 1
	v_cndmask_b32_e64 v100, v228, v37, s[0:1]
	v_readlane_b32 s0, v254, 40
	v_readlane_b32 s1, v254, 41
	s_nop 1
	v_cndmask_b32_e64 v101, v228, v53, s[0:1]
	v_readlane_b32 s0, v254, 42
	v_readlane_b32 s1, v254, 43
	s_nop 1
	v_cndmask_b32_e64 v66, v228, v38, s[0:1]
	v_readlane_b32 s0, v254, 44
	v_readlane_b32 s1, v254, 45
	s_nop 1
	v_cndmask_b32_e64 v67, v228, v54, s[0:1]
	v_readlane_b32 s0, v254, 46
	v_readlane_b32 s1, v254, 47
	s_nop 1
	v_cndmask_b32_e64 v53, v228, v39, s[0:1]
	v_readlane_b32 s0, v254, 48
	v_readlane_b32 s1, v254, 49
	s_nop 1
	v_cndmask_b32_e64 v54, v228, v55, s[0:1]
	v_readlane_b32 s0, v254, 50
	v_readlane_b32 s1, v254, 51
	s_nop 1
	v_cndmask_b32_e64 v51, v228, v40, s[0:1]
	v_readlane_b32 s0, v254, 52
	v_readlane_b32 s1, v254, 53
	s_nop 1
	v_cndmask_b32_e64 v52, v228, v56, s[0:1]
	v_readlane_b32 s0, v254, 54
	v_readlane_b32 s1, v254, 55
	s_nop 1
	v_cndmask_b32_e64 v49, v228, v41, s[0:1]
	v_readlane_b32 s0, v254, 56
	v_readlane_b32 s1, v254, 57
	s_nop 1
	v_cndmask_b32_e64 v50, v228, v57, s[0:1]
	v_readlane_b32 s0, v254, 58
	v_readlane_b32 s1, v254, 59
	s_nop 1
	v_cndmask_b32_e64 v42, v228, v42, s[0:1]
	v_readlane_b32 s0, v254, 60
	v_readlane_b32 s1, v254, 61
	s_nop 1
	v_cndmask_b32_e64 v48, v228, v58, s[0:1]
	v_readlane_b32 s0, v254, 62
	v_readlane_b32 s1, v254, 63
	s_nop 1
	v_cndmask_b32_e64 v40, v228, v43, s[0:1]
	v_readlane_b32 s0, v255, 0
	v_readlane_b32 s1, v255, 1
	v_max_f32_e32 v43, v111, v111
	s_nop 0
	v_cndmask_b32_e64 v41, v228, v59, s[0:1]
	v_readlane_b32 s0, v255, 2
	v_readlane_b32 s1, v255, 3
	s_nop 1
	v_cndmask_b32_e64 v38, v228, v44, s[0:1]
	v_max_f32_e32 v44, v110, v110
	v_max_f32_e32 v43, v44, v43
	v_max3_f32 v43, v43, v108, v109
	v_max3_f32 v43, v43, v106, v107
	v_readlane_b32 s0, v255, 4
	v_max3_f32 v43, v43, v104, v105
	v_readlane_b32 s1, v255, 5
	v_max3_f32 v43, v43, v102, v103
	v_max3_f32 v43, v43, v100, v101
	v_cndmask_b32_e64 v39, v228, v60, s[0:1]
	v_readlane_b32 s0, v255, 6
	v_readlane_b32 s1, v255, 7
	v_max3_f32 v43, v43, v66, v67
	v_max3_f32 v43, v43, v53, v54
	v_cndmask_b32_e64 v34, v228, v45, s[0:1]
	v_readlane_b32 s0, v255, 8
	v_readlane_b32 s1, v255, 9
	v_max3_f32 v43, v43, v51, v52
	v_max3_f32 v43, v43, v49, v50
	v_cndmask_b32_e64 v36, v228, v61, s[0:1]
	v_readlane_b32 s0, v255, 10
	v_readlane_b32 s1, v255, 11
	v_max3_f32 v43, v43, v42, v48
	v_max3_f32 v43, v43, v40, v41
	v_cndmask_b32_e64 v35, v228, v46, s[0:1]
	v_readlane_b32 s0, v255, 12
	v_readlane_b32 s1, v255, 13
	v_max3_f32 v43, v43, v38, v39
	v_max3_f32 v43, v43, v34, v36
	v_cndmask_b32_e64 v37, v228, v62, s[0:1]
	v_max3_f32 v43, v43, v35, v37
	v_max3_f32 v43, v43, v33, v32
	v_fmamk_f32 v43, v43, 0x3e38aa3b, v64
	ds_bpermute_b32 v44, v126, v43
	s_waitcnt lgkmcnt(0)
	v_max3_f32 v43, v136, v43, v44
	v_cmp_gt_f32_e32 vcc, v43, v136
	s_cbranch_vccz .LBB0_385
	v_sub_f32_e32 v44, v136, v43
	v_exp_f32_e32 v44, v44
	s_nop 0
	v_mul_f32_e32 v135, v135, v44
	v_mul_f32_e32 v30, v30, v44
	v_mul_f32_e32 v31, v31, v44
	v_mul_f32_e32 v28, v28, v44
	v_mul_f32_e32 v29, v29, v44
	v_mul_f32_e32 v26, v26, v44
	v_mul_f32_e32 v27, v27, v44
	v_mul_f32_e32 v24, v24, v44
	v_mul_f32_e32 v25, v25, v44
	v_mul_f32_e32 v22, v22, v44
	v_mul_f32_e32 v23, v23, v44
	v_mul_f32_e32 v20, v20, v44
	v_mul_f32_e32 v21, v21, v44
	v_mul_f32_e32 v18, v18, v44
	v_mul_f32_e32 v19, v19, v44
	v_mul_f32_e32 v16, v16, v44
	v_mul_f32_e32 v17, v17, v44
	v_mul_f32_e32 v14, v14, v44
	v_mul_f32_e32 v15, v15, v44
	v_mul_f32_e32 v12, v12, v44
	v_mul_f32_e32 v13, v13, v44
	v_mul_f32_e32 v10, v10, v44
	v_mul_f32_e32 v11, v11, v44
	v_mul_f32_e32 v8, v8, v44
	v_mul_f32_e32 v9, v9, v44
	v_mul_f32_e32 v6, v6, v44
	v_mul_f32_e32 v7, v7, v44
	v_mul_f32_e32 v4, v4, v44
	v_mul_f32_e32 v5, v5, v44
	v_mul_f32_e32 v2, v2, v44
	v_mul_f32_e32 v3, v3, v44
	v_mul_f32_e32 v0, v0, v44
	v_mul_f32_e32 v1, v1, v44
	s_branch .LBB0_385

; __device__ __forceinline__ float bflo(unsigned u) { return __uint_as_float(u << 16); }
; __device__ __forceinline__ float bfhi(unsigned u) { return __uint_as_float(u & 0xffff0000u); }
; __device__ __forceinline__ void ln_panel(int pm, const float* resf, const bf16* rlo, const bf16* dlt, float* xo, const float* gam, const float* bet, bf16* xb, bf16* wlo, bool fin, float alpha) {
;     ...
; #pragma unroll 4
;     for (int r = wave * 32; r < wave * 32 + 32; ++r) {
;         const size_t grow = (size_t)(pm * 256 + r) * DM + 4 * lane, prow = (size_t)r * DM + 4 * lane;
;         f32x4 v[4]; float s = 0.f;
; #pragma unroll
;         for (int j = 0; j < 4; ++j) { f32x4 x; const u32x2 d = *(const u32x2*)(dlt + prow + 256 * j);
;             if (resf) x = *(const f32x4*)(resf + grow + 256 * j);
;             else { const u32x2 h = *(const u32x2*)(xb + grow + 256 * j), l = *(const u32x2*)(rlo + prow + 256 * j);
;                    x = (f32x4){bflo(h.x) + bflo(l.x), bfhi(h.x) + bfhi(l.x), bflo(h.y) + bflo(l.y), bfhi(h.y) + bfhi(l.y)}; }
;             v[j] = (f32x4){x.x * alpha + bflo(d.x), x.y * alpha + bfhi(d.x), x.z * alpha + bflo(d.y), x.w * alpha + bfhi(d.y)}; s += (v[j].x + v[j].y) + (v[j].z + v[j].w); }
;         const float mean = wave_sum(s) * (1.f / DM); float s2 = 0.f;
; #pragma unroll
;         for (int j = 0; j < 4; ++j) { v[j] = v[j] - mean; s2 += (v[j].x * v[j].x + v[j].y * v[j].y) + (v[j].z * v[j].z + v[j].w * v[j].w); }
;         const float rstd = 1.f / sqrtf(wave_sum(s2) * (1.f / DM) + LN_EPS);
.Lmy_ln1h_loop:
	s_waitcnt vmcnt(28)
.Lmy_ln1h_entry:
	v_lshlrev_b32_e32 v150, 16, v66
	v_and_b32_e32 v151, 0xffff0000, v66
	v_lshlrev_b32_e32 v152, 16, v74
	v_and_b32_e32 v153, 0xffff0000, v74
	v_add_f32_e32 v150, v150, v152
	v_add_f32_e32 v151, v151, v153
	v_lshlrev_b32_e32 v152, 16, v82
	v_and_b32_e32 v153, 0xffff0000, v82
	v_fma_f32 v114, v150, v164, v152
	v_fma_f32 v115, v151, v165, v153
	v_lshlrev_b32_e32 v150, 16, v67
	v_and_b32_e32 v151, 0xffff0000, v67
	v_lshlrev_b32_e32 v152, 16, v75
	v_and_b32_e32 v153, 0xffff0000, v75
	v_add_f32_e32 v150, v150, v152
	v_add_f32_e32 v151, v151, v153
	v_lshlrev_b32_e32 v152, 16, v83
	v_and_b32_e32 v153, 0xffff0000, v83
	v_fma_f32 v116, v150, v164, v152
	v_fma_f32 v117, v151, v165, v153
	v_lshlrev_b32_e32 v150, 16, v68
	v_and_b32_e32 v151, 0xffff0000, v68
	v_lshlrev_b32_e32 v152, 16, v76
	v_and_b32_e32 v153, 0xffff0000, v76
	v_add_f32_e32 v150, v150, v152
	v_add_f32_e32 v151, v151, v153
	v_lshlrev_b32_e32 v152, 16, v84
	v_and_b32_e32 v153, 0xffff0000, v84
	v_fma_f32 v118, v150, v164, v152
	v_fma_f32 v119, v151, v165, v153
	v_lshlrev_b32_e32 v150, 16, v69
	v_and_b32_e32 v151, 0xffff0000, v69
	v_lshlrev_b32_e32 v152, 16, v77
	v_and_b32_e32 v153, 0xffff0000, v77
	v_add_f32_e32 v150, v150, v152
	v_add_f32_e32 v151, v151, v153
	v_lshlrev_b32_e32 v152, 16, v85
	v_and_b32_e32 v153, 0xffff0000, v85
	v_fma_f32 v120, v150, v164, v152
	v_fma_f32 v121, v151, v165, v153
	v_lshlrev_b32_e32 v150, 16, v70
	v_and_b32_e32 v151, 0xffff0000, v70
	v_lshlrev_b32_e32 v152, 16, v78
	v_and_b32_e32 v153, 0xffff0000, v78
	v_add_f32_e32 v150, v150, v152
	v_add_f32_e32 v151, v151, v153
	v_lshlrev_b32_e32 v152, 16, v86
	v_and_b32_e32 v153, 0xffff0000, v86
	v_fma_f32 v122, v150, v164, v152
	v_fma_f32 v123, v151, v165, v153
	v_lshlrev_b32_e32 v150, 16, v71
	v_and_b32_e32 v151, 0xffff0000, v71
	v_lshlrev_b32_e32 v152, 16, v79
	v_and_b32_e32 v153, 0xffff0000, v79
	v_add_f32_e32 v150, v150, v152
	v_add_f32_e32 v151, v151, v153
	v_lshlrev_b32_e32 v152, 16, v87
	v_and_b32_e32 v153, 0xffff0000, v87
	v_fma_f32 v124, v150, v164, v152
	v_fma_f32 v125, v151, v165, v153
	v_lshlrev_b32_e32 v150, 16, v72
	v_and_b32_e32 v151, 0xffff0000, v72
	v_lshlrev_b32_e32 v152, 16, v80
	v_and_b32_e32 v153, 0xffff0000, v80
	v_add_f32_e32 v150, v150, v152
	v_add_f32_e32 v151, v151, v153
	v_lshlrev_b32_e32 v152, 16, v88
	v_and_b32_e32 v153, 0xffff0000, v88
	v_fma_f32 v126, v150, v164, v152
	v_fma_f32 v127, v151, v165, v153
	v_lshlrev_b32_e32 v150, 16, v73
	v_and_b32_e32 v151, 0xffff0000, v73
	v_lshlrev_b32_e32 v152, 16, v81
	v_and_b32_e32 v153, 0xffff0000, v81
	v_add_f32_e32 v150, v150, v152
	v_add_f32_e32 v151, v151, v153
	v_lshlrev_b32_e32 v152, 16, v89
	v_and_b32_e32 v153, 0xffff0000, v89
	v_fma_f32 v128, v150, v164, v152
	v_fma_f32 v129, v151, v165, v153
	s_add_i32 s0, s98, 2
	s_min_u32 s0, s0, 31
	s_lshl_b32 s0, s0, 11
	s_mov_b32 s1, 0
	v_lshl_add_u64 v[184:185], s[0:1], 0, v[178:179]
	v_lshl_add_u64 v[186:187], s[0:1], 0, v[172:173]
	v_lshl_add_u64 v[188:189], s[0:1], 0, v[176:177]
	global_load_dwordx2 v[82:83], v[184:185], off offset:-1024
	global_load_dwordx2 v[84:85], v[184:185], off offset:-512
	global_load_dwordx2 v[86:87], v[184:185], off offset:0
	global_load_dwordx2 v[88:89], v[184:185], off offset:512
	global_load_dwordx2 v[66:67], v[186:187], off offset:0
	global_load_dwordx2 v[68:69], v[186:187], off offset:512
	global_load_dwordx2 v[70:71], v[186:187], off offset:1024
	global_load_dwordx2 v[72:73], v[186:187], off offset:1536
	global_load_dwordx2 v[74:75], v[188:189], off offset:0
	global_load_dwordx2 v[76:77], v[188:189], off offset:512
	global_load_dwordx2 v[78:79], v[188:189], off offset:1024
	global_load_dwordx2 v[80:81], v[188:189], off offset:1536
	v_add_f32_e32 v154, v114, v116
	v_add_f32_e32 v155, v115, v117
	v_add_f32_e32 v156, v118, v120
	v_add_f32_e32 v157, v119, v121
	v_add_f32_e32 v154, v154, v156
	v_add_f32_e32 v155, v155, v157
	v_add_f32_e32 v156, v122, v124
	v_add_f32_e32 v157, v123, v125
	v_add_f32_e32 v154, v154, v156
	v_add_f32_e32 v155, v155, v157
	v_add_f32_e32 v156, v126, v128
	v_add_f32_e32 v157, v127, v129
	v_add_f32_e32 v154, v154, v156
	v_add_f32_e32 v155, v155, v157
	v_add_f32_e32 v154, v154, v155
	s_nop 1
	v_add_f32_dpp v160, v154, v154 quad_perm:[1,0,3,2] row_mask:0xf bank_mask:0xf
	s_nop 1
	v_add_f32_dpp v160, v160, v160 quad_perm:[2,3,0,1] row_mask:0xf bank_mask:0xf
	s_nop 1
	v_add_f32_dpp v160, v160, v160 row_half_mirror row_mask:0xf bank_mask:0xf
	s_nop 1
	v_add_f32_dpp v160, v160, v160 row_mirror row_mask:0xf bank_mask:0xf
	s_nop 1
	v_add_f32_dpp v160, v160, v160 row_bcast:15 row_mask:0xa bank_mask:0xf
	s_nop 1
	v_add_f32_dpp v160, v160, v160 row_bcast:31 row_mask:0xc bank_mask:0xf
	s_nop 1
	v_readlane_b32 s0, v160, 63
	s_nop 2
	v_mov_b32_e32 v170, s0
	v_mul_f32_e32 v156, 0xba800000, v170
	v_mul_f32_e32 v157, 0xba800000, v170
	v_add_f32_e32 v114, v114, v156
	v_add_f32_e32 v115, v115, v157
	v_add_f32_e32 v116, v116, v156
	v_add_f32_e32 v117, v117, v157
	v_add_f32_e32 v118, v118, v156
	v_add_f32_e32 v119, v119, v157
	v_add_f32_e32 v120, v120, v156
	v_add_f32_e32 v121, v121, v157
	v_add_f32_e32 v122, v122, v156
	v_add_f32_e32 v123, v123, v157
	v_add_f32_e32 v124, v124, v156
	v_add_f32_e32 v125, v125, v157
	v_add_f32_e32 v126, v126, v156
	v_add_f32_e32 v127, v127, v157
	v_add_f32_e32 v128, v128, v156
	v_add_f32_e32 v129, v129, v157
	v_mul_f32_e32 v154, v114, v114
	v_mul_f32_e32 v155, v115, v115
	v_fma_f32 v154, v116, v116, v154
	v_fma_f32 v155, v117, v117, v155
	v_fma_f32 v154, v118, v118, v154
	v_fma_f32 v155, v119, v119, v155
	v_fma_f32 v154, v120, v120, v154
	v_fma_f32 v155, v121, v121, v155
; __device__ __forceinline__ unsigned pk2(float lo, float hi) { return pg8::cvt_pk_bf16(lo, hi); }
; __device__ __forceinline__ float bflo(unsigned u) { return __uint_as_float(u << 16); }
; __device__ __forceinline__ float bfhi(unsigned u) { return __uint_as_float(u & 0xffff0000u); }
; __device__ __forceinline__ void ln_panel(int pm, const float* resf, const bf16* rlo, const bf16* dlt, float* xo, const float* gam, const float* bet, bf16* xb, bf16* wlo, bool fin, float alpha) {
;     ...
; #pragma unroll
;         for (int j = 0; j < 4; ++j) { v[j] = v[j] - mean; s2 += (v[j].x * v[j].x + v[j].y * v[j].y) + (v[j].z * v[j].z + v[j].w * v[j].w); }
;         const float rstd = 1.f / sqrtf(wave_sum(s2) * (1.f / DM) + LN_EPS);
; #pragma unroll
;         for (int j = 0; j < 4; ++j) { const f32x4 o = v[j] * rstd * gv[j] + bv[j];
;             if (fin) *(f32x4*)(xo + grow + 256 * j) = o;
;             else { u32x2 w; w.x = pk2(o.x, o.y); w.y = pk2(o.z, o.w); *(u32x2*)(xb + grow + 256 * j) = w;
;                    u32x2 q; q.x = pk2(o.x - bflo(w.x), o.y - bfhi(w.x)); q.y = pk2(o.z - bflo(w.y), o.w - bfhi(w.y)); *(u32x2*)(wlo + prow + 256 * j) = q; } }
	v_fma_f32 v154, v122, v122, v154
	v_fma_f32 v155, v123, v123, v155
	v_fma_f32 v154, v124, v124, v154
	v_fma_f32 v155, v125, v125, v155
	v_fma_f32 v154, v126, v126, v154
	v_fma_f32 v155, v127, v127, v155
	v_fma_f32 v154, v128, v128, v154
	v_fma_f32 v155, v129, v129, v155
	v_add_f32_e32 v154, v154, v155
	s_nop 1
	v_add_f32_dpp v160, v154, v154 quad_perm:[1,0,3,2] row_mask:0xf bank_mask:0xf
	s_nop 1
	v_add_f32_dpp v160, v160, v160 quad_perm:[2,3,0,1] row_mask:0xf bank_mask:0xf
	s_nop 1
	v_add_f32_dpp v160, v160, v160 row_half_mirror row_mask:0xf bank_mask:0xf
	s_nop 1
	v_add_f32_dpp v160, v160, v160 row_mirror row_mask:0xf bank_mask:0xf
	s_nop 1
	v_add_f32_dpp v160, v160, v160 row_bcast:15 row_mask:0xa bank_mask:0xf
	s_nop 1
	v_add_f32_dpp v160, v160, v160 row_bcast:31 row_mask:0xc bank_mask:0xf
	s_nop 1
	v_readlane_b32 s0, v160, 63
	s_nop 2
	v_mov_b32_e32 v170, s0
	v_fmamk_f32 v154, v170, 0x3a800000, v166
	s_mov_b32 s0, 0xf800000
	v_mul_f32_e32 v155, 0x4f800000, v154
	v_cmp_gt_f32_e32 vcc, s0, v154
	s_nop 1
	v_cndmask_b32_e32 v154, v154, v155, vcc
	v_sqrt_f32_e32 v155, v154
	s_nop 0
	v_add_u32_e32 v156, -1, v155
	v_fma_f32 v157, -v156, v155, v154
	v_cmp_ge_f32_e64 s[0:1], 0, v157
	v_add_u32_e32 v157, 1, v155
	s_nop 0
	v_cndmask_b32_e64 v156, v155, v156, s[0:1]
	v_fma_f32 v155, -v157, v155, v154
	v_cmp_lt_f32_e64 s[0:1], 0, v155
	s_nop 1
	v_cndmask_b32_e64 v155, v156, v157, s[0:1]
	v_mul_f32_e32 v156, 0x37800000, v155
	v_cndmask_b32_e32 v155, v155, v156, vcc
	v_cmp_class_f32_e32 vcc, v154, v167
	s_nop 1
	v_cndmask_b32_e32 v154, v155, v154, vcc
	v_div_scale_f32 v155, s[0:1], v154, v154, 1.0
	v_rcp_f32_e32 v156, v155
	s_nop 0
	v_fma_f32 v157, -v155, v156, 1.0
	v_fmac_f32_e32 v156, v157, v156
	v_div_scale_f32 v157, vcc, 1.0, v154, 1.0
	v_mul_f32_e32 v158, v157, v156
	v_fma_f32 v159, -v155, v158, v157
	v_fmac_f32_e32 v158, v159, v156
	v_fma_f32 v155, -v155, v158, v157
	s_nop 0
	v_div_fmas_f32 v155, v155, v156, v158
	v_div_fixup_f32 v168, v155, v154, 1.0
	s_add_i32 s0, s98, 0
	s_lshl_b32 s0, s0, 11
	s_mov_b32 s1, 0
	v_lshl_add_u64 v[184:185], s[0:1], 0, v[172:173]
	v_lshl_add_u64 v[186:187], s[0:1], 0, v[180:181]
	v_mul_f32_e32 v150, v114, v168
	v_mul_f32_e32 v151, v115, v168
	v_fma_f32 v150, v0, v150, v8
	v_fma_f32 v151, v1, v151, v9
	v_mul_f32_e32 v152, v116, v168
	v_mul_f32_e32 v153, v117, v168
	v_fma_f32 v152, v2, v152, v10
	v_fma_f32 v153, v3, v153, v11
	v_cvt_pk_bf16_f32 v190, v150, v151
	v_cvt_pk_bf16_f32 v191, v152, v153
	v_lshlrev_b32_e32 v154, 16, v190
	v_and_b32_e32 v155, 0xffff0000, v190
	v_sub_f32_e32 v150, v150, v154
	v_sub_f32_e32 v151, v151, v155
	v_cvt_pk_bf16_f32 v198, v150, v151
	v_lshlrev_b32_e32 v154, 16, v191
	v_and_b32_e32 v155, 0xffff0000, v191
	v_sub_f32_e32 v152, v152, v154
	v_sub_f32_e32 v153, v153, v155
	v_cvt_pk_bf16_f32 v199, v152, v153
	v_mul_f32_e32 v150, v118, v168
	v_mul_f32_e32 v151, v119, v168
	v_fma_f32 v150, v4, v150, v12
	v_fma_f32 v151, v5, v151, v13
	v_mul_f32_e32 v152, v120, v168
	v_mul_f32_e32 v153, v121, v168
	v_fma_f32 v152, v6, v152, v14
	v_fma_f32 v153, v7, v153, v15
	v_cvt_pk_bf16_f32 v192, v150, v151
	v_cvt_pk_bf16_f32 v193, v152, v153
	v_lshlrev_b32_e32 v154, 16, v192
	v_and_b32_e32 v155, 0xffff0000, v192
	v_sub_f32_e32 v150, v150, v154
	v_sub_f32_e32 v151, v151, v155
	v_cvt_pk_bf16_f32 v200, v150, v151
	v_lshlrev_b32_e32 v154, 16, v193
	v_and_b32_e32 v155, 0xffff0000, v193
	v_sub_f32_e32 v152, v152, v154
	v_sub_f32_e32 v153, v153, v155
	v_cvt_pk_bf16_f32 v201, v152, v153
	v_mul_f32_e32 v150, v122, v168
	v_mul_f32_e32 v151, v123, v168
	v_fma_f32 v150, v16, v150, v24
	v_fma_f32 v151, v17, v151, v25
	v_mul_f32_e32 v152, v124, v168
	v_mul_f32_e32 v153, v125, v168
	v_fma_f32 v152, v18, v152, v26
	v_fma_f32 v153, v19, v153, v27
	v_cvt_pk_bf16_f32 v194, v150, v151
	v_cvt_pk_bf16_f32 v195, v152, v153
	v_lshlrev_b32_e32 v154, 16, v194
	v_and_b32_e32 v155, 0xffff0000, v194
	v_sub_f32_e32 v150, v150, v154
	v_sub_f32_e32 v151, v151, v155
	v_cvt_pk_bf16_f32 v202, v150, v151
	v_lshlrev_b32_e32 v154, 16, v195
	v_and_b32_e32 v155, 0xffff0000, v195
	v_sub_f32_e32 v152, v152, v154
	v_sub_f32_e32 v153, v153, v155
	v_cvt_pk_bf16_f32 v203, v152, v153
	v_mul_f32_e32 v150, v126, v168
	v_mul_f32_e32 v151, v127, v168
	v_fma_f32 v150, v20, v150, v28
	v_fma_f32 v151, v21, v151, v29
	v_mul_f32_e32 v152, v128, v168
	v_mul_f32_e32 v153, v129, v168
	v_fma_f32 v152, v22, v152, v30
	v_fma_f32 v153, v23, v153, v31
	v_cvt_pk_bf16_f32 v196, v150, v151
	v_cvt_pk_bf16_f32 v197, v152, v153
	v_lshlrev_b32_e32 v154, 16, v196
	v_and_b32_e32 v155, 0xffff0000, v196
	v_sub_f32_e32 v150, v150, v154
	v_sub_f32_e32 v151, v151, v155
	v_cvt_pk_bf16_f32 v204, v150, v151
	v_lshlrev_b32_e32 v154, 16, v197
	v_and_b32_e32 v155, 0xffff0000, v197
	v_sub_f32_e32 v152, v152, v154
	v_sub_f32_e32 v153, v153, v155
	v_cvt_pk_bf16_f32 v205, v152, v153
	global_store_dwordx2 v[184:185], v[190:191], off offset:0
	global_store_dwordx2 v[184:185], v[192:193], off offset:512
	global_store_dwordx2 v[184:185], v[194:195], off offset:1024
	global_store_dwordx2 v[184:185], v[196:197], off offset:1536
	global_store_dwordx2 v[186:187], v[198:199], off offset:0
	global_store_dwordx2 v[186:187], v[200:201], off offset:512
	global_store_dwordx2 v[186:187], v[202:203], off offset:1024
	global_store_dwordx2 v[186:187], v[204:205], off offset:1536
	s_waitcnt vmcnt(20)
; __device__ __forceinline__ float bflo(unsigned u) { return __uint_as_float(u << 16); }
; __device__ __forceinline__ float bfhi(unsigned u) { return __uint_as_float(u & 0xffff0000u); }
; __device__ __forceinline__ void ln_panel(int pm, const float* resf, const bf16* rlo, const bf16* dlt, float* xo, const float* gam, const float* bet, bf16* xb, bf16* wlo, bool fin, float alpha) {
;     ...
;         for (int j = 0; j < 4; ++j) { f32x4 x; const u32x2 d = *(const u32x2*)(dlt + prow + 256 * j);
;             if (resf) x = *(const f32x4*)(resf + grow + 256 * j);
;             else { const u32x2 h = *(const u32x2*)(xb + grow + 256 * j), l = *(const u32x2*)(rlo + prow + 256 * j);
;                    x = (f32x4){bflo(h.x) + bflo(l.x), bfhi(h.x) + bfhi(l.x), bflo(h.y) + bflo(l.y), bfhi(h.y) + bfhi(l.y)}; }
;             v[j] = (f32x4){x.x * alpha + bflo(d.x), x.y * alpha + bfhi(d.x), x.z * alpha + bflo(d.y), x.w * alpha + bfhi(d.y)}; s += (v[j].x + v[j].y) + (v[j].z + v[j].w); }
;         const float mean = wave_sum(s) * (1.f / DM); float s2 = 0.f;
	v_lshlrev_b32_e32 v150, 16, v90
	v_and_b32_e32 v151, 0xffff0000, v90
	v_lshlrev_b32_e32 v152, 16, v98
	v_and_b32_e32 v153, 0xffff0000, v98
	v_add_f32_e32 v150, v150, v152
	v_add_f32_e32 v151, v151, v153
	v_lshlrev_b32_e32 v152, 16, v106
	v_and_b32_e32 v153, 0xffff0000, v106
	v_fma_f32 v114, v150, v164, v152
	v_fma_f32 v115, v151, v165, v153
	v_lshlrev_b32_e32 v150, 16, v91
	v_and_b32_e32 v151, 0xffff0000, v91
	v_lshlrev_b32_e32 v152, 16, v99
	v_and_b32_e32 v153, 0xffff0000, v99
	v_add_f32_e32 v150, v150, v152
	v_add_f32_e32 v151, v151, v153
	v_lshlrev_b32_e32 v152, 16, v107
	v_and_b32_e32 v153, 0xffff0000, v107
	v_fma_f32 v116, v150, v164, v152
	v_fma_f32 v117, v151, v165, v153
	v_lshlrev_b32_e32 v150, 16, v92
	v_and_b32_e32 v151, 0xffff0000, v92
	v_lshlrev_b32_e32 v152, 16, v100
	v_and_b32_e32 v153, 0xffff0000, v100
	v_add_f32_e32 v150, v150, v152
	v_add_f32_e32 v151, v151, v153
	v_lshlrev_b32_e32 v152, 16, v108
	v_and_b32_e32 v153, 0xffff0000, v108
	v_fma_f32 v118, v150, v164, v152
	v_fma_f32 v119, v151, v165, v153
	v_lshlrev_b32_e32 v150, 16, v93
	v_and_b32_e32 v151, 0xffff0000, v93
	v_lshlrev_b32_e32 v152, 16, v101
	v_and_b32_e32 v153, 0xffff0000, v101
	v_add_f32_e32 v150, v150, v152
	v_add_f32_e32 v151, v151, v153
	v_lshlrev_b32_e32 v152, 16, v109
	v_and_b32_e32 v153, 0xffff0000, v109
	v_fma_f32 v120, v150, v164, v152
	v_fma_f32 v121, v151, v165, v153
	v_lshlrev_b32_e32 v150, 16, v94
	v_and_b32_e32 v151, 0xffff0000, v94
	v_lshlrev_b32_e32 v152, 16, v102
	v_and_b32_e32 v153, 0xffff0000, v102
	v_add_f32_e32 v150, v150, v152
	v_add_f32_e32 v151, v151, v153
	v_lshlrev_b32_e32 v152, 16, v110
	v_and_b32_e32 v153, 0xffff0000, v110
	v_fma_f32 v122, v150, v164, v152
	v_fma_f32 v123, v151, v165, v153
	v_lshlrev_b32_e32 v150, 16, v95
	v_and_b32_e32 v151, 0xffff0000, v95
	v_lshlrev_b32_e32 v152, 16, v103
	v_and_b32_e32 v153, 0xffff0000, v103
	v_add_f32_e32 v150, v150, v152
	v_add_f32_e32 v151, v151, v153
	v_lshlrev_b32_e32 v152, 16, v111
	v_and_b32_e32 v153, 0xffff0000, v111
	v_fma_f32 v124, v150, v164, v152
	v_fma_f32 v125, v151, v165, v153
	v_lshlrev_b32_e32 v150, 16, v96
	v_and_b32_e32 v151, 0xffff0000, v96
	v_lshlrev_b32_e32 v152, 16, v104
	v_and_b32_e32 v153, 0xffff0000, v104
	v_add_f32_e32 v150, v150, v152
	v_add_f32_e32 v151, v151, v153
	v_lshlrev_b32_e32 v152, 16, v112
	v_and_b32_e32 v153, 0xffff0000, v112
	v_fma_f32 v126, v150, v164, v152
	v_fma_f32 v127, v151, v165, v153
	v_lshlrev_b32_e32 v150, 16, v97
	v_and_b32_e32 v151, 0xffff0000, v97
	v_lshlrev_b32_e32 v152, 16, v105
	v_and_b32_e32 v153, 0xffff0000, v105
	v_add_f32_e32 v150, v150, v152
	v_add_f32_e32 v151, v151, v153
	v_lshlrev_b32_e32 v152, 16, v113
	v_and_b32_e32 v153, 0xffff0000, v113
	v_fma_f32 v128, v150, v164, v152
	v_fma_f32 v129, v151, v165, v153
	s_add_i32 s0, s98, 3
	s_min_u32 s0, s0, 31
	s_lshl_b32 s0, s0, 11
	s_mov_b32 s1, 0
	v_lshl_add_u64 v[184:185], s[0:1], 0, v[178:179]
	v_lshl_add_u64 v[186:187], s[0:1], 0, v[172:173]
	v_lshl_add_u64 v[188:189], s[0:1], 0, v[176:177]
	global_load_dwordx2 v[106:107], v[184:185], off offset:-1024
	global_load_dwordx2 v[108:109], v[184:185], off offset:-512
	global_load_dwordx2 v[110:111], v[184:185], off offset:0
	global_load_dwordx2 v[112:113], v[184:185], off offset:512
	global_load_dwordx2 v[90:91], v[186:187], off offset:0
	global_load_dwordx2 v[92:93], v[186:187], off offset:512
	global_load_dwordx2 v[94:95], v[186:187], off offset:1024
	global_load_dwordx2 v[96:97], v[186:187], off offset:1536
	global_load_dwordx2 v[98:99], v[188:189], off offset:0
	global_load_dwordx2 v[100:101], v[188:189], off offset:512
	global_load_dwordx2 v[102:103], v[188:189], off offset:1024
	global_load_dwordx2 v[104:105], v[188:189], off offset:1536
	v_add_f32_e32 v154, v114, v116
	v_add_f32_e32 v155, v115, v117
	v_add_f32_e32 v156, v118, v120
	v_add_f32_e32 v157, v119, v121
	v_add_f32_e32 v154, v154, v156
	v_add_f32_e32 v155, v155, v157
	v_add_f32_e32 v156, v122, v124
	v_add_f32_e32 v157, v123, v125
	v_add_f32_e32 v154, v154, v156
	v_add_f32_e32 v155, v155, v157
	v_add_f32_e32 v156, v126, v128
	v_add_f32_e32 v157, v127, v129
	v_add_f32_e32 v154, v154, v156
	v_add_f32_e32 v155, v155, v157
	v_add_f32_e32 v154, v154, v155
	s_nop 1
	v_add_f32_dpp v160, v154, v154 quad_perm:[1,0,3,2] row_mask:0xf bank_mask:0xf
	s_nop 1
	v_add_f32_dpp v160, v160, v160 quad_perm:[2,3,0,1] row_mask:0xf bank_mask:0xf
	s_nop 1
	v_add_f32_dpp v160, v160, v160 row_half_mirror row_mask:0xf bank_mask:0xf
	s_nop 1
	v_add_f32_dpp v160, v160, v160 row_mirror row_mask:0xf bank_mask:0xf
	s_nop 1
	v_add_f32_dpp v160, v160, v160 row_bcast:15 row_mask:0xa bank_mask:0xf
	s_nop 1
	v_add_f32_dpp v160, v160, v160 row_bcast:31 row_mask:0xc bank_mask:0xf
	s_nop 1
	v_readlane_b32 s0, v160, 63
	s_nop 2
	v_mov_b32_e32 v170, s0
	v_mul_f32_e32 v156, 0xba800000, v170
	v_mul_f32_e32 v157, 0xba800000, v170
	v_add_f32_e32 v114, v114, v156
	v_add_f32_e32 v115, v115, v157
	v_add_f32_e32 v116, v116, v156
	v_add_f32_e32 v117, v117, v157
	v_add_f32_e32 v118, v118, v156
	v_add_f32_e32 v119, v119, v157
	v_add_f32_e32 v120, v120, v156
	v_add_f32_e32 v121, v121, v157
	v_add_f32_e32 v122, v122, v156
	v_add_f32_e32 v123, v123, v157
	v_add_f32_e32 v124, v124, v156
	v_add_f32_e32 v125, v125, v157
	v_add_f32_e32 v126, v126, v156
	v_add_f32_e32 v127, v127, v157
	v_add_f32_e32 v128, v128, v156
	v_add_f32_e32 v129, v129, v157
	v_mul_f32_e32 v154, v114, v114
	v_mul_f32_e32 v155, v115, v115
	v_fma_f32 v154, v116, v116, v154
	v_fma_f32 v155, v117, v117, v155
	v_fma_f32 v154, v118, v118, v154
; __device__ __forceinline__ unsigned pk2(float lo, float hi) { return pg8::cvt_pk_bf16(lo, hi); }
; __device__ __forceinline__ float bflo(unsigned u) { return __uint_as_float(u << 16); }
; __device__ __forceinline__ float bfhi(unsigned u) { return __uint_as_float(u & 0xffff0000u); }
; __device__ __forceinline__ void ln_panel(int pm, const float* resf, const bf16* rlo, const bf16* dlt, float* xo, const float* gam, const float* bet, bf16* xb, bf16* wlo, bool fin, float alpha) {
;     ...
; #pragma unroll
;         for (int j = 0; j < 4; ++j) { v[j] = v[j] - mean; s2 += (v[j].x * v[j].x + v[j].y * v[j].y) + (v[j].z * v[j].z + v[j].w * v[j].w); }
;         const float rstd = 1.f / sqrtf(wave_sum(s2) * (1.f / DM) + LN_EPS);
; #pragma unroll
;         for (int j = 0; j < 4; ++j) { const f32x4 o = v[j] * rstd * gv[j] + bv[j];
;             if (fin) *(f32x4*)(xo + grow + 256 * j) = o;
;             else { u32x2 w; w.x = pk2(o.x, o.y); w.y = pk2(o.z, o.w); *(u32x2*)(xb + grow + 256 * j) = w;
;                    u32x2 q; q.x = pk2(o.x - bflo(w.x), o.y - bfhi(w.x)); q.y = pk2(o.z - bflo(w.y), o.w - bfhi(w.y)); *(u32x2*)(wlo + prow + 256 * j) = q; } }
	v_fma_f32 v155, v119, v119, v155
	v_fma_f32 v154, v120, v120, v154
	v_fma_f32 v155, v121, v121, v155
	v_fma_f32 v154, v122, v122, v154
	v_fma_f32 v155, v123, v123, v155
	v_fma_f32 v154, v124, v124, v154
	v_fma_f32 v155, v125, v125, v155
	v_fma_f32 v154, v126, v126, v154
	v_fma_f32 v155, v127, v127, v155
	v_fma_f32 v154, v128, v128, v154
	v_fma_f32 v155, v129, v129, v155
	v_add_f32_e32 v154, v154, v155
	s_nop 1
	v_add_f32_dpp v160, v154, v154 quad_perm:[1,0,3,2] row_mask:0xf bank_mask:0xf
	s_nop 1
	v_add_f32_dpp v160, v160, v160 quad_perm:[2,3,0,1] row_mask:0xf bank_mask:0xf
	s_nop 1
	v_add_f32_dpp v160, v160, v160 row_half_mirror row_mask:0xf bank_mask:0xf
	s_nop 1
	v_add_f32_dpp v160, v160, v160 row_mirror row_mask:0xf bank_mask:0xf
	s_nop 1
	v_add_f32_dpp v160, v160, v160 row_bcast:15 row_mask:0xa bank_mask:0xf
	s_nop 1
	v_add_f32_dpp v160, v160, v160 row_bcast:31 row_mask:0xc bank_mask:0xf
	s_nop 1
	v_readlane_b32 s0, v160, 63
	s_nop 2
	v_mov_b32_e32 v170, s0
	v_fmamk_f32 v154, v170, 0x3a800000, v166
	s_mov_b32 s0, 0xf800000
	v_mul_f32_e32 v155, 0x4f800000, v154
	v_cmp_gt_f32_e32 vcc, s0, v154
	s_nop 1
	v_cndmask_b32_e32 v154, v154, v155, vcc
	v_sqrt_f32_e32 v155, v154
	s_nop 0
	v_add_u32_e32 v156, -1, v155
	v_fma_f32 v157, -v156, v155, v154
	v_cmp_ge_f32_e64 s[0:1], 0, v157
	v_add_u32_e32 v157, 1, v155
	s_nop 0
	v_cndmask_b32_e64 v156, v155, v156, s[0:1]
	v_fma_f32 v155, -v157, v155, v154
	v_cmp_lt_f32_e64 s[0:1], 0, v155
	s_nop 1
	v_cndmask_b32_e64 v155, v156, v157, s[0:1]
	v_mul_f32_e32 v156, 0x37800000, v155
	v_cndmask_b32_e32 v155, v155, v156, vcc
	v_cmp_class_f32_e32 vcc, v154, v167
	s_nop 1
	v_cndmask_b32_e32 v154, v155, v154, vcc
	v_div_scale_f32 v155, s[0:1], v154, v154, 1.0
	v_rcp_f32_e32 v156, v155
	s_nop 0
	v_fma_f32 v157, -v155, v156, 1.0
	v_fmac_f32_e32 v156, v157, v156
	v_div_scale_f32 v157, vcc, 1.0, v154, 1.0
	v_mul_f32_e32 v158, v157, v156
	v_fma_f32 v159, -v155, v158, v157
	v_fmac_f32_e32 v158, v159, v156
	v_fma_f32 v155, -v155, v158, v157
	s_nop 0
	v_div_fmas_f32 v155, v155, v156, v158
	v_div_fixup_f32 v168, v155, v154, 1.0
	s_add_i32 s0, s98, 1
	s_lshl_b32 s0, s0, 11
	s_mov_b32 s1, 0
	v_lshl_add_u64 v[184:185], s[0:1], 0, v[172:173]
	v_lshl_add_u64 v[186:187], s[0:1], 0, v[180:181]
	v_mul_f32_e32 v150, v114, v168
	v_mul_f32_e32 v151, v115, v168
	v_fma_f32 v150, v0, v150, v8
	v_fma_f32 v151, v1, v151, v9
	v_mul_f32_e32 v152, v116, v168
	v_mul_f32_e32 v153, v117, v168
	v_fma_f32 v152, v2, v152, v10
	v_fma_f32 v153, v3, v153, v11
	v_cvt_pk_bf16_f32 v190, v150, v151
	v_cvt_pk_bf16_f32 v191, v152, v153
	v_lshlrev_b32_e32 v154, 16, v190
	v_and_b32_e32 v155, 0xffff0000, v190
	v_sub_f32_e32 v150, v150, v154
	v_sub_f32_e32 v151, v151, v155
	v_cvt_pk_bf16_f32 v198, v150, v151
	v_lshlrev_b32_e32 v154, 16, v191
	v_and_b32_e32 v155, 0xffff0000, v191
	v_sub_f32_e32 v152, v152, v154
	v_sub_f32_e32 v153, v153, v155
	v_cvt_pk_bf16_f32 v199, v152, v153
	v_mul_f32_e32 v150, v118, v168
	v_mul_f32_e32 v151, v119, v168
	v_fma_f32 v150, v4, v150, v12
	v_fma_f32 v151, v5, v151, v13
	v_mul_f32_e32 v152, v120, v168
	v_mul_f32_e32 v153, v121, v168
	v_fma_f32 v152, v6, v152, v14
	v_fma_f32 v153, v7, v153, v15
	v_cvt_pk_bf16_f32 v192, v150, v151
	v_cvt_pk_bf16_f32 v193, v152, v153
	v_lshlrev_b32_e32 v154, 16, v192
	v_and_b32_e32 v155, 0xffff0000, v192
	v_sub_f32_e32 v150, v150, v154
	v_sub_f32_e32 v151, v151, v155
	v_cvt_pk_bf16_f32 v200, v150, v151
	v_lshlrev_b32_e32 v154, 16, v193
	v_and_b32_e32 v155, 0xffff0000, v193
	v_sub_f32_e32 v152, v152, v154
	v_sub_f32_e32 v153, v153, v155
	v_cvt_pk_bf16_f32 v201, v152, v153
	v_mul_f32_e32 v150, v122, v168
	v_mul_f32_e32 v151, v123, v168
	v_fma_f32 v150, v16, v150, v24
	v_fma_f32 v151, v17, v151, v25
	v_mul_f32_e32 v152, v124, v168
	v_mul_f32_e32 v153, v125, v168
	v_fma_f32 v152, v18, v152, v26
	v_fma_f32 v153, v19, v153, v27
	v_cvt_pk_bf16_f32 v194, v150, v151
	v_cvt_pk_bf16_f32 v195, v152, v153
	v_lshlrev_b32_e32 v154, 16, v194
	v_and_b32_e32 v155, 0xffff0000, v194
	v_sub_f32_e32 v150, v150, v154
	v_sub_f32_e32 v151, v151, v155
	v_cvt_pk_bf16_f32 v202, v150, v151
	v_lshlrev_b32_e32 v154, 16, v195
	v_and_b32_e32 v155, 0xffff0000, v195
	v_sub_f32_e32 v152, v152, v154
	v_sub_f32_e32 v153, v153, v155
	v_cvt_pk_bf16_f32 v203, v152, v153
	v_mul_f32_e32 v150, v126, v168
	v_mul_f32_e32 v151, v127, v168
	v_fma_f32 v150, v20, v150, v28
	v_fma_f32 v151, v21, v151, v29
	v_mul_f32_e32 v152, v128, v168
	v_mul_f32_e32 v153, v129, v168
	v_fma_f32 v152, v22, v152, v30
	v_fma_f32 v153, v23, v153, v31
	v_cvt_pk_bf16_f32 v196, v150, v151
	v_cvt_pk_bf16_f32 v197, v152, v153
	v_lshlrev_b32_e32 v154, 16, v196
	v_and_b32_e32 v155, 0xffff0000, v196
	v_sub_f32_e32 v150, v150, v154
	v_sub_f32_e32 v151, v151, v155
	v_cvt_pk_bf16_f32 v204, v150, v151
	v_lshlrev_b32_e32 v154, 16, v197
	v_and_b32_e32 v155, 0xffff0000, v197
	v_sub_f32_e32 v152, v152, v154
	v_sub_f32_e32 v153, v153, v155
	v_cvt_pk_bf16_f32 v205, v152, v153
	global_store_dwordx2 v[184:185], v[190:191], off offset:0
	global_store_dwordx2 v[184:185], v[192:193], off offset:512
	global_store_dwordx2 v[184:185], v[194:195], off offset:1024
	global_store_dwordx2 v[184:185], v[196:197], off offset:1536
	global_store_dwordx2 v[186:187], v[198:199], off offset:0
	global_store_dwordx2 v[186:187], v[200:201], off offset:512
	global_store_dwordx2 v[186:187], v[202:203], off offset:1024
	global_store_dwordx2 v[186:187], v[204:205], off offset:1536
	s_add_i32 s98, s98, 2
	s_cmp_lt_u32 s98, 32
	s_cbranch_scc1 .Lmy_ln1h_loop
	s_waitcnt vmcnt(0)
	s_branch .LBB0_557

; __device__ __forceinline__ float bflo(unsigned u) { return __uint_as_float(u << 16); }
; __device__ __forceinline__ float bfhi(unsigned u) { return __uint_as_float(u & 0xffff0000u); }
; __device__ __forceinline__ void ln_panel(int pm, const float* resf, const bf16* rlo, const bf16* dlt, float* xo, const float* gam, const float* bet, bf16* xb, bf16* wlo, bool fin, float alpha) {
;     ...
; #pragma unroll 4
;     for (int r = wave * 32; r < wave * 32 + 32; ++r) {
;         const size_t grow = (size_t)(pm * 256 + r) * DM + 4 * lane, prow = (size_t)r * DM + 4 * lane;
;         f32x4 v[4]; float s = 0.f;
; #pragma unroll
;         for (int j = 0; j < 4; ++j) { f32x4 x; const u32x2 d = *(const u32x2*)(dlt + prow + 256 * j);
;             if (resf) x = *(const f32x4*)(resf + grow + 256 * j);
;             else { const u32x2 h = *(const u32x2*)(xb + grow + 256 * j), l = *(const u32x2*)(rlo + prow + 256 * j);
;                    x = (f32x4){bflo(h.x) + bflo(l.x), bfhi(h.x) + bfhi(l.x), bflo(h.y) + bflo(l.y), bfhi(h.y) + bfhi(l.y)}; }
;             v[j] = (f32x4){x.x * alpha + bflo(d.x), x.y * alpha + bfhi(d.x), x.z * alpha + bflo(d.y), x.w * alpha + bfhi(d.y)}; s += (v[j].x + v[j].y) + (v[j].z + v[j].w); }
;         const float mean = wave_sum(s) * (1.f / DM); float s2 = 0.f;
; #pragma unroll
;         for (int j = 0; j < 4; ++j) { v[j] = v[j] - mean; s2 += (v[j].x * v[j].x + v[j].y * v[j].y) + (v[j].z * v[j].z + v[j].w * v[j].w); }
;         const float rstd = 1.f / sqrtf(wave_sum(s2) * (1.f / DM) + LN_EPS);
.Lmy_ln1r_loop:
	s_waitcnt vmcnt(24)
.Lmy_ln1r_entry:
	v_lshlrev_b32_e32 v152, 16, v82
	v_and_b32_e32 v153, 0xffff0000, v82
	v_fma_f32 v114, v66, v164, v152
	v_fma_f32 v115, v67, v165, v153
	v_lshlrev_b32_e32 v152, 16, v83
	v_and_b32_e32 v153, 0xffff0000, v83
	v_fma_f32 v116, v68, v164, v152
	v_fma_f32 v117, v69, v165, v153
	v_lshlrev_b32_e32 v152, 16, v84
	v_and_b32_e32 v153, 0xffff0000, v84
	v_fma_f32 v118, v70, v164, v152
	v_fma_f32 v119, v71, v165, v153
	v_lshlrev_b32_e32 v152, 16, v85
	v_and_b32_e32 v153, 0xffff0000, v85
	v_fma_f32 v120, v72, v164, v152
	v_fma_f32 v121, v73, v165, v153
	v_lshlrev_b32_e32 v152, 16, v86
	v_and_b32_e32 v153, 0xffff0000, v86
	v_fma_f32 v122, v74, v164, v152
	v_fma_f32 v123, v75, v165, v153
	v_lshlrev_b32_e32 v152, 16, v87
	v_and_b32_e32 v153, 0xffff0000, v87
	v_fma_f32 v124, v76, v164, v152
	v_fma_f32 v125, v77, v165, v153
	v_lshlrev_b32_e32 v152, 16, v88
	v_and_b32_e32 v153, 0xffff0000, v88
	v_fma_f32 v126, v78, v164, v152
	v_fma_f32 v127, v79, v165, v153
	v_lshlrev_b32_e32 v152, 16, v89
	v_and_b32_e32 v153, 0xffff0000, v89
	v_fma_f32 v128, v80, v164, v152
	v_fma_f32 v129, v81, v165, v153
	s_add_i32 s0, s98, 2
	s_min_u32 s0, s0, 31
	s_lshl_b32 s0, s0, 11
	s_mov_b32 s1, 0
	v_lshl_add_u64 v[184:185], s[0:1], 0, v[178:179]
	v_lshl_add_u64 v[186:187], s[0:1], 1, v[182:183]
	global_load_dwordx2 v[82:83], v[184:185], off offset:-1024
	global_load_dwordx2 v[84:85], v[184:185], off offset:-512
	global_load_dwordx2 v[86:87], v[184:185], off offset:0
	global_load_dwordx2 v[88:89], v[184:185], off offset:512
	global_load_dwordx4 v[66:69], v[186:187], off offset:0
	global_load_dwordx4 v[70:73], v[186:187], off offset:1024
	global_load_dwordx4 v[74:77], v[186:187], off offset:2048
	global_load_dwordx4 v[78:81], v[186:187], off offset:3072
	v_add_f32_e32 v154, v114, v116
	v_add_f32_e32 v155, v115, v117
	v_add_f32_e32 v156, v118, v120
	v_add_f32_e32 v157, v119, v121
	v_add_f32_e32 v154, v154, v156
	v_add_f32_e32 v155, v155, v157
	v_add_f32_e32 v156, v122, v124
	v_add_f32_e32 v157, v123, v125
	v_add_f32_e32 v154, v154, v156
	v_add_f32_e32 v155, v155, v157
	v_add_f32_e32 v156, v126, v128
	v_add_f32_e32 v157, v127, v129
	v_add_f32_e32 v154, v154, v156
	v_add_f32_e32 v155, v155, v157
	v_add_f32_e32 v154, v154, v155
	s_nop 1
	v_add_f32_dpp v160, v154, v154 quad_perm:[1,0,3,2] row_mask:0xf bank_mask:0xf
	s_nop 1
	v_add_f32_dpp v160, v160, v160 quad_perm:[2,3,0,1] row_mask:0xf bank_mask:0xf
	s_nop 1
	v_add_f32_dpp v160, v160, v160 row_half_mirror row_mask:0xf bank_mask:0xf
	s_nop 1
	v_add_f32_dpp v160, v160, v160 row_mirror row_mask:0xf bank_mask:0xf
	s_nop 1
	v_add_f32_dpp v160, v160, v160 row_bcast:15 row_mask:0xa bank_mask:0xf
	s_nop 1
	v_add_f32_dpp v160, v160, v160 row_bcast:31 row_mask:0xc bank_mask:0xf
	s_nop 1
	v_readlane_b32 s0, v160, 63
	s_nop 2
	v_mov_b32_e32 v170, s0
	v_mul_f32_e32 v156, 0xba800000, v170
	v_mul_f32_e32 v157, 0xba800000, v170
	v_add_f32_e32 v114, v114, v156
	v_add_f32_e32 v115, v115, v157
	v_add_f32_e32 v116, v116, v156
	v_add_f32_e32 v117, v117, v157
	v_add_f32_e32 v118, v118, v156
	v_add_f32_e32 v119, v119, v157
	v_add_f32_e32 v120, v120, v156
	v_add_f32_e32 v121, v121, v157
	v_add_f32_e32 v122, v122, v156
	v_add_f32_e32 v123, v123, v157
	v_add_f32_e32 v124, v124, v156
	v_add_f32_e32 v125, v125, v157
	v_add_f32_e32 v126, v126, v156
	v_add_f32_e32 v127, v127, v157
	v_add_f32_e32 v128, v128, v156
	v_add_f32_e32 v129, v129, v157
	v_mul_f32_e32 v154, v114, v114
	v_mul_f32_e32 v155, v115, v115
	v_fma_f32 v154, v116, v116, v154
	v_fma_f32 v155, v117, v117, v155
	v_fma_f32 v154, v118, v118, v154
	v_fma_f32 v155, v119, v119, v155
	v_fma_f32 v154, v120, v120, v154
	v_fma_f32 v155, v121, v121, v155
	v_fma_f32 v154, v122, v122, v154
	v_fma_f32 v155, v123, v123, v155
	v_fma_f32 v154, v124, v124, v154
	v_fma_f32 v155, v125, v125, v155
	v_fma_f32 v154, v126, v126, v154
	v_fma_f32 v155, v127, v127, v155
	v_fma_f32 v154, v128, v128, v154
	v_fma_f32 v155, v129, v129, v155
	v_add_f32_e32 v154, v154, v155
	s_nop 1
	v_add_f32_dpp v160, v154, v154 quad_perm:[1,0,3,2] row_mask:0xf bank_mask:0xf
	s_nop 1
	v_add_f32_dpp v160, v160, v160 quad_perm:[2,3,0,1] row_mask:0xf bank_mask:0xf
	s_nop 1
	v_add_f32_dpp v160, v160, v160 row_half_mirror row_mask:0xf bank_mask:0xf
	s_nop 1
	v_add_f32_dpp v160, v160, v160 row_mirror row_mask:0xf bank_mask:0xf
	s_nop 1
	v_add_f32_dpp v160, v160, v160 row_bcast:15 row_mask:0xa bank_mask:0xf
	s_nop 1
	v_add_f32_dpp v160, v160, v160 row_bcast:31 row_mask:0xc bank_mask:0xf
	s_nop 1
	v_readlane_b32 s0, v160, 63
	s_nop 2
	v_mov_b32_e32 v170, s0
	v_fmamk_f32 v154, v170, 0x3a800000, v166
	s_mov_b32 s0, 0xf800000
	v_mul_f32_e32 v155, 0x4f800000, v154
	v_cmp_gt_f32_e32 vcc, s0, v154
	s_nop 1
	v_cndmask_b32_e32 v154, v154, v155, vcc
	v_sqrt_f32_e32 v155, v154
	s_nop 0
	v_add_u32_e32 v156, -1, v155
	v_fma_f32 v157, -v156, v155, v154
	v_cmp_ge_f32_e64 s[0:1], 0, v157
	v_add_u32_e32 v157, 1, v155
	s_nop 0
	v_cndmask_b32_e64 v156, v155, v156, s[0:1]
	v_fma_f32 v155, -v157, v155, v154
	v_cmp_lt_f32_e64 s[0:1], 0, v155
	s_nop 1
	v_cndmask_b32_e64 v155, v156, v157, s[0:1]
	v_mul_f32_e32 v156, 0x37800000, v155
	v_cndmask_b32_e32 v155, v155, v156, vcc
	v_cmp_class_f32_e32 vcc, v154, v167
	s_nop 1
	v_cndmask_b32_e32 v154, v155, v154, vcc
	v_div_scale_f32 v155, s[0:1], v154, v154, 1.0
	v_rcp_f32_e32 v156, v155
	s_nop 0
	v_fma_f32 v157, -v155, v156, 1.0
	v_fmac_f32_e32 v156, v157, v156
	v_div_scale_f32 v157, vcc, 1.0, v154, 1.0
	v_mul_f32_e32 v158, v157, v156
	v_fma_f32 v159, -v155, v158, v157
	v_fmac_f32_e32 v158, v159, v156
	v_fma_f32 v155, -v155, v158, v157
	s_nop 0
	v_div_fmas_f32 v155, v155, v156, v158
; __device__ __forceinline__ unsigned pk2(float lo, float hi) { return pg8::cvt_pk_bf16(lo, hi); }
; __device__ __forceinline__ float bflo(unsigned u) { return __uint_as_float(u << 16); }
; __device__ __forceinline__ float bfhi(unsigned u) { return __uint_as_float(u & 0xffff0000u); }
; __device__ __forceinline__ void ln_panel(int pm, const float* resf, const bf16* rlo, const bf16* dlt, float* xo, const float* gam, const float* bet, bf16* xb, bf16* wlo, bool fin, float alpha) {
;     ...
;         for (int j = 0; j < 4; ++j) { f32x4 x; const u32x2 d = *(const u32x2*)(dlt + prow + 256 * j);
;             if (resf) x = *(const f32x4*)(resf + grow + 256 * j);
;             else { const u32x2 h = *(const u32x2*)(xb + grow + 256 * j), l = *(const u32x2*)(rlo + prow + 256 * j);
;                    x = (f32x4){bflo(h.x) + bflo(l.x), bfhi(h.x) + bfhi(l.x), bflo(h.y) + bflo(l.y), bfhi(h.y) + bfhi(l.y)}; }
;             v[j] = (f32x4){x.x * alpha + bflo(d.x), x.y * alpha + bfhi(d.x), x.z * alpha + bflo(d.y), x.w * alpha + bfhi(d.y)}; s += (v[j].x + v[j].y) + (v[j].z + v[j].w); }
;         const float mean = wave_sum(s) * (1.f / DM); float s2 = 0.f;
; #pragma unroll
;         for (int j = 0; j < 4; ++j) { v[j] = v[j] - mean; s2 += (v[j].x * v[j].x + v[j].y * v[j].y) + (v[j].z * v[j].z + v[j].w * v[j].w); }
;         const float rstd = 1.f / sqrtf(wave_sum(s2) * (1.f / DM) + LN_EPS);
; #pragma unroll
;         for (int j = 0; j < 4; ++j) { const f32x4 o = v[j] * rstd * gv[j] + bv[j];
;             if (fin) *(f32x4*)(xo + grow + 256 * j) = o;
;             else { u32x2 w; w.x = pk2(o.x, o.y); w.y = pk2(o.z, o.w); *(u32x2*)(xb + grow + 256 * j) = w;
;                    u32x2 q; q.x = pk2(o.x - bflo(w.x), o.y - bfhi(w.x)); q.y = pk2(o.z - bflo(w.y), o.w - bfhi(w.y)); *(u32x2*)(wlo + prow + 256 * j) = q; } }
	v_div_fixup_f32 v168, v155, v154, 1.0
	s_add_i32 s0, s98, 0
	s_lshl_b32 s0, s0, 11
	s_mov_b32 s1, 0
	v_lshl_add_u64 v[184:185], s[0:1], 0, v[172:173]
	v_lshl_add_u64 v[186:187], s[0:1], 0, v[180:181]
	v_mul_f32_e32 v150, v114, v168
	v_mul_f32_e32 v151, v115, v168
	v_fma_f32 v150, v0, v150, v8
	v_fma_f32 v151, v1, v151, v9
	v_mul_f32_e32 v152, v116, v168
	v_mul_f32_e32 v153, v117, v168
	v_fma_f32 v152, v2, v152, v10
	v_fma_f32 v153, v3, v153, v11
	v_cvt_pk_bf16_f32 v190, v150, v151
	v_cvt_pk_bf16_f32 v191, v152, v153
	v_lshlrev_b32_e32 v154, 16, v190
	v_and_b32_e32 v155, 0xffff0000, v190
	v_sub_f32_e32 v150, v150, v154
	v_sub_f32_e32 v151, v151, v155
	v_cvt_pk_bf16_f32 v198, v150, v151
	v_lshlrev_b32_e32 v154, 16, v191
	v_and_b32_e32 v155, 0xffff0000, v191
	v_sub_f32_e32 v152, v152, v154
	v_sub_f32_e32 v153, v153, v155
	v_cvt_pk_bf16_f32 v199, v152, v153
	v_mul_f32_e32 v150, v118, v168
	v_mul_f32_e32 v151, v119, v168
	v_fma_f32 v150, v4, v150, v12
	v_fma_f32 v151, v5, v151, v13
	v_mul_f32_e32 v152, v120, v168
	v_mul_f32_e32 v153, v121, v168
	v_fma_f32 v152, v6, v152, v14
	v_fma_f32 v153, v7, v153, v15
	v_cvt_pk_bf16_f32 v192, v150, v151
	v_cvt_pk_bf16_f32 v193, v152, v153
	v_lshlrev_b32_e32 v154, 16, v192
	v_and_b32_e32 v155, 0xffff0000, v192
	v_sub_f32_e32 v150, v150, v154
	v_sub_f32_e32 v151, v151, v155
	v_cvt_pk_bf16_f32 v200, v150, v151
	v_lshlrev_b32_e32 v154, 16, v193
	v_and_b32_e32 v155, 0xffff0000, v193
	v_sub_f32_e32 v152, v152, v154
	v_sub_f32_e32 v153, v153, v155
	v_cvt_pk_bf16_f32 v201, v152, v153
	v_mul_f32_e32 v150, v122, v168
	v_mul_f32_e32 v151, v123, v168
	v_fma_f32 v150, v16, v150, v24
	v_fma_f32 v151, v17, v151, v25
	v_mul_f32_e32 v152, v124, v168
	v_mul_f32_e32 v153, v125, v168
	v_fma_f32 v152, v18, v152, v26
	v_fma_f32 v153, v19, v153, v27
	v_cvt_pk_bf16_f32 v194, v150, v151
	v_cvt_pk_bf16_f32 v195, v152, v153
	v_lshlrev_b32_e32 v154, 16, v194
	v_and_b32_e32 v155, 0xffff0000, v194
	v_sub_f32_e32 v150, v150, v154
	v_sub_f32_e32 v151, v151, v155
	v_cvt_pk_bf16_f32 v202, v150, v151
	v_lshlrev_b32_e32 v154, 16, v195
	v_and_b32_e32 v155, 0xffff0000, v195
	v_sub_f32_e32 v152, v152, v154
	v_sub_f32_e32 v153, v153, v155
	v_cvt_pk_bf16_f32 v203, v152, v153
	v_mul_f32_e32 v150, v126, v168
	v_mul_f32_e32 v151, v127, v168
	v_fma_f32 v150, v20, v150, v28
	v_fma_f32 v151, v21, v151, v29
	v_mul_f32_e32 v152, v128, v168
	v_mul_f32_e32 v153, v129, v168
	v_fma_f32 v152, v22, v152, v30
	v_fma_f32 v153, v23, v153, v31
	v_cvt_pk_bf16_f32 v196, v150, v151
	v_cvt_pk_bf16_f32 v197, v152, v153
	v_lshlrev_b32_e32 v154, 16, v196
	v_and_b32_e32 v155, 0xffff0000, v196
	v_sub_f32_e32 v150, v150, v154
	v_sub_f32_e32 v151, v151, v155
	v_cvt_pk_bf16_f32 v204, v150, v151
	v_lshlrev_b32_e32 v154, 16, v197
	v_and_b32_e32 v155, 0xffff0000, v197
	v_sub_f32_e32 v152, v152, v154
	v_sub_f32_e32 v153, v153, v155
	v_cvt_pk_bf16_f32 v205, v152, v153
	global_store_dwordx2 v[184:185], v[190:191], off offset:0
	global_store_dwordx2 v[184:185], v[192:193], off offset:512
	global_store_dwordx2 v[184:185], v[194:195], off offset:1024
	global_store_dwordx2 v[184:185], v[196:197], off offset:1536
	global_store_dwordx2 v[186:187], v[198:199], off offset:0
	global_store_dwordx2 v[186:187], v[200:201], off offset:512
	global_store_dwordx2 v[186:187], v[202:203], off offset:1024
	global_store_dwordx2 v[186:187], v[204:205], off offset:1536
	s_waitcnt vmcnt(16)
	v_lshlrev_b32_e32 v152, 16, v106
	v_and_b32_e32 v153, 0xffff0000, v106
	v_fma_f32 v114, v90, v164, v152
	v_fma_f32 v115, v91, v165, v153
	v_lshlrev_b32_e32 v152, 16, v107
	v_and_b32_e32 v153, 0xffff0000, v107
	v_fma_f32 v116, v92, v164, v152
	v_fma_f32 v117, v93, v165, v153
	v_lshlrev_b32_e32 v152, 16, v108
	v_and_b32_e32 v153, 0xffff0000, v108
	v_fma_f32 v118, v94, v164, v152
	v_fma_f32 v119, v95, v165, v153
	v_lshlrev_b32_e32 v152, 16, v109
	v_and_b32_e32 v153, 0xffff0000, v109
	v_fma_f32 v120, v96, v164, v152
	v_fma_f32 v121, v97, v165, v153
	v_lshlrev_b32_e32 v152, 16, v110
	v_and_b32_e32 v153, 0xffff0000, v110
	v_fma_f32 v122, v98, v164, v152
	v_fma_f32 v123, v99, v165, v153
	v_lshlrev_b32_e32 v152, 16, v111
	v_and_b32_e32 v153, 0xffff0000, v111
	v_fma_f32 v124, v100, v164, v152
	v_fma_f32 v125, v101, v165, v153
	v_lshlrev_b32_e32 v152, 16, v112
	v_and_b32_e32 v153, 0xffff0000, v112
	v_fma_f32 v126, v102, v164, v152
	v_fma_f32 v127, v103, v165, v153
	v_lshlrev_b32_e32 v152, 16, v113
	v_and_b32_e32 v153, 0xffff0000, v113
	v_fma_f32 v128, v104, v164, v152
	v_fma_f32 v129, v105, v165, v153
	s_add_i32 s0, s98, 3
	s_min_u32 s0, s0, 31
	s_lshl_b32 s0, s0, 11
	s_mov_b32 s1, 0
	v_lshl_add_u64 v[184:185], s[0:1], 0, v[178:179]
	v_lshl_add_u64 v[186:187], s[0:1], 1, v[182:183]
	global_load_dwordx2 v[106:107], v[184:185], off offset:-1024
	global_load_dwordx2 v[108:109], v[184:185], off offset:-512
	global_load_dwordx2 v[110:111], v[184:185], off offset:0
	global_load_dwordx2 v[112:113], v[184:185], off offset:512
	global_load_dwordx4 v[90:93], v[186:187], off offset:0
	global_load_dwordx4 v[94:97], v[186:187], off offset:1024
	global_load_dwordx4 v[98:101], v[186:187], off offset:2048
	global_load_dwordx4 v[102:105], v[186:187], off offset:3072
	v_add_f32_e32 v154, v114, v116
	v_add_f32_e32 v155, v115, v117
	v_add_f32_e32 v156, v118, v120
	v_add_f32_e32 v157, v119, v121
	v_add_f32_e32 v154, v154, v156
	v_add_f32_e32 v155, v155, v157
	v_add_f32_e32 v156, v122, v124
	v_add_f32_e32 v157, v123, v125
	v_add_f32_e32 v154, v154, v156
	v_add_f32_e32 v155, v155, v157
	v_add_f32_e32 v156, v126, v128
	v_add_f32_e32 v157, v127, v129
	v_add_f32_e32 v154, v154, v156
	v_add_f32_e32 v155, v155, v157
	v_add_f32_e32 v154, v154, v155
; __device__ __forceinline__ unsigned pk2(float lo, float hi) { return pg8::cvt_pk_bf16(lo, hi); }
; __device__ __forceinline__ float bflo(unsigned u) { return __uint_as_float(u << 16); }
; __device__ __forceinline__ float bfhi(unsigned u) { return __uint_as_float(u & 0xffff0000u); }
; __device__ __forceinline__ void ln_panel(int pm, const float* resf, const bf16* rlo, const bf16* dlt, float* xo, const float* gam, const float* bet, bf16* xb, bf16* wlo, bool fin, float alpha) {
;     ...
; #pragma unroll
;         for (int j = 0; j < 4; ++j) { v[j] = v[j] - mean; s2 += (v[j].x * v[j].x + v[j].y * v[j].y) + (v[j].z * v[j].z + v[j].w * v[j].w); }
;         const float rstd = 1.f / sqrtf(wave_sum(s2) * (1.f / DM) + LN_EPS);
; #pragma unroll
;         for (int j = 0; j < 4; ++j) { const f32x4 o = v[j] * rstd * gv[j] + bv[j];
;             if (fin) *(f32x4*)(xo + grow + 256 * j) = o;
;             else { u32x2 w; w.x = pk2(o.x, o.y); w.y = pk2(o.z, o.w); *(u32x2*)(xb + grow + 256 * j) = w;
;                    u32x2 q; q.x = pk2(o.x - bflo(w.x), o.y - bfhi(w.x)); q.y = pk2(o.z - bflo(w.y), o.w - bfhi(w.y)); *(u32x2*)(wlo + prow + 256 * j) = q; } }
	s_nop 1
	v_add_f32_dpp v160, v154, v154 quad_perm:[1,0,3,2] row_mask:0xf bank_mask:0xf
	s_nop 1
	v_add_f32_dpp v160, v160, v160 quad_perm:[2,3,0,1] row_mask:0xf bank_mask:0xf
	s_nop 1
	v_add_f32_dpp v160, v160, v160 row_half_mirror row_mask:0xf bank_mask:0xf
	s_nop 1
	v_add_f32_dpp v160, v160, v160 row_mirror row_mask:0xf bank_mask:0xf
	s_nop 1
	v_add_f32_dpp v160, v160, v160 row_bcast:15 row_mask:0xa bank_mask:0xf
	s_nop 1
	v_add_f32_dpp v160, v160, v160 row_bcast:31 row_mask:0xc bank_mask:0xf
	s_nop 1
	v_readlane_b32 s0, v160, 63
	s_nop 2
	v_mov_b32_e32 v170, s0
	v_mul_f32_e32 v156, 0xba800000, v170
	v_mul_f32_e32 v157, 0xba800000, v170
	v_add_f32_e32 v114, v114, v156
	v_add_f32_e32 v115, v115, v157
	v_add_f32_e32 v116, v116, v156
	v_add_f32_e32 v117, v117, v157
	v_add_f32_e32 v118, v118, v156
	v_add_f32_e32 v119, v119, v157
	v_add_f32_e32 v120, v120, v156
	v_add_f32_e32 v121, v121, v157
	v_add_f32_e32 v122, v122, v156
	v_add_f32_e32 v123, v123, v157
	v_add_f32_e32 v124, v124, v156
	v_add_f32_e32 v125, v125, v157
	v_add_f32_e32 v126, v126, v156
	v_add_f32_e32 v127, v127, v157
	v_add_f32_e32 v128, v128, v156
	v_add_f32_e32 v129, v129, v157
	v_mul_f32_e32 v154, v114, v114
	v_mul_f32_e32 v155, v115, v115
	v_fma_f32 v154, v116, v116, v154
	v_fma_f32 v155, v117, v117, v155
	v_fma_f32 v154, v118, v118, v154
	v_fma_f32 v155, v119, v119, v155
	v_fma_f32 v154, v120, v120, v154
	v_fma_f32 v155, v121, v121, v155
	v_fma_f32 v154, v122, v122, v154
	v_fma_f32 v155, v123, v123, v155
	v_fma_f32 v154, v124, v124, v154
	v_fma_f32 v155, v125, v125, v155
	v_fma_f32 v154, v126, v126, v154
	v_fma_f32 v155, v127, v127, v155
	v_fma_f32 v154, v128, v128, v154
	v_fma_f32 v155, v129, v129, v155
	v_add_f32_e32 v154, v154, v155
	s_nop 1
	v_add_f32_dpp v160, v154, v154 quad_perm:[1,0,3,2] row_mask:0xf bank_mask:0xf
	s_nop 1
	v_add_f32_dpp v160, v160, v160 quad_perm:[2,3,0,1] row_mask:0xf bank_mask:0xf
	s_nop 1
	v_add_f32_dpp v160, v160, v160 row_half_mirror row_mask:0xf bank_mask:0xf
	s_nop 1
	v_add_f32_dpp v160, v160, v160 row_mirror row_mask:0xf bank_mask:0xf
	s_nop 1
	v_add_f32_dpp v160, v160, v160 row_bcast:15 row_mask:0xa bank_mask:0xf
	s_nop 1
	v_add_f32_dpp v160, v160, v160 row_bcast:31 row_mask:0xc bank_mask:0xf
	s_nop 1
	v_readlane_b32 s0, v160, 63
	s_nop 2
	v_mov_b32_e32 v170, s0
	v_fmamk_f32 v154, v170, 0x3a800000, v166
	s_mov_b32 s0, 0xf800000
	v_mul_f32_e32 v155, 0x4f800000, v154
	v_cmp_gt_f32_e32 vcc, s0, v154
	s_nop 1
	v_cndmask_b32_e32 v154, v154, v155, vcc
	v_sqrt_f32_e32 v155, v154
	s_nop 0
	v_add_u32_e32 v156, -1, v155
	v_fma_f32 v157, -v156, v155, v154
	v_cmp_ge_f32_e64 s[0:1], 0, v157
	v_add_u32_e32 v157, 1, v155
	s_nop 0
	v_cndmask_b32_e64 v156, v155, v156, s[0:1]
	v_fma_f32 v155, -v157, v155, v154
	v_cmp_lt_f32_e64 s[0:1], 0, v155
	s_nop 1
	v_cndmask_b32_e64 v155, v156, v157, s[0:1]
	v_mul_f32_e32 v156, 0x37800000, v155
	v_cndmask_b32_e32 v155, v155, v156, vcc
	v_cmp_class_f32_e32 vcc, v154, v167
	s_nop 1
	v_cndmask_b32_e32 v154, v155, v154, vcc
	v_div_scale_f32 v155, s[0:1], v154, v154, 1.0
	v_rcp_f32_e32 v156, v155
	s_nop 0
	v_fma_f32 v157, -v155, v156, 1.0
	v_fmac_f32_e32 v156, v157, v156
	v_div_scale_f32 v157, vcc, 1.0, v154, 1.0
	v_mul_f32_e32 v158, v157, v156
	v_fma_f32 v159, -v155, v158, v157
	v_fmac_f32_e32 v158, v159, v156
	v_fma_f32 v155, -v155, v158, v157
	s_nop 0
	v_div_fmas_f32 v155, v155, v156, v158
	v_div_fixup_f32 v168, v155, v154, 1.0
	s_add_i32 s0, s98, 1
	s_lshl_b32 s0, s0, 11
	s_mov_b32 s1, 0
	v_lshl_add_u64 v[184:185], s[0:1], 0, v[172:173]
	v_lshl_add_u64 v[186:187], s[0:1], 0, v[180:181]
	v_mul_f32_e32 v150, v114, v168
	v_mul_f32_e32 v151, v115, v168
	v_fma_f32 v150, v0, v150, v8
	v_fma_f32 v151, v1, v151, v9
	v_mul_f32_e32 v152, v116, v168
	v_mul_f32_e32 v153, v117, v168
	v_fma_f32 v152, v2, v152, v10
	v_fma_f32 v153, v3, v153, v11
	v_cvt_pk_bf16_f32 v190, v150, v151
	v_cvt_pk_bf16_f32 v191, v152, v153
	v_lshlrev_b32_e32 v154, 16, v190
	v_and_b32_e32 v155, 0xffff0000, v190
	v_sub_f32_e32 v150, v150, v154
	v_sub_f32_e32 v151, v151, v155
	v_cvt_pk_bf16_f32 v198, v150, v151
	v_lshlrev_b32_e32 v154, 16, v191
	v_and_b32_e32 v155, 0xffff0000, v191
	v_sub_f32_e32 v152, v152, v154
	v_sub_f32_e32 v153, v153, v155
	v_cvt_pk_bf16_f32 v199, v152, v153
	v_mul_f32_e32 v150, v118, v168
	v_mul_f32_e32 v151, v119, v168
	v_fma_f32 v150, v4, v150, v12
	v_fma_f32 v151, v5, v151, v13
	v_mul_f32_e32 v152, v120, v168
	v_mul_f32_e32 v153, v121, v168
	v_fma_f32 v152, v6, v152, v14
	v_fma_f32 v153, v7, v153, v15
	v_cvt_pk_bf16_f32 v192, v150, v151
	v_cvt_pk_bf16_f32 v193, v152, v153
	v_lshlrev_b32_e32 v154, 16, v192
	v_and_b32_e32 v155, 0xffff0000, v192
	v_sub_f32_e32 v150, v150, v154
	v_sub_f32_e32 v151, v151, v155
	v_cvt_pk_bf16_f32 v200, v150, v151
	v_lshlrev_b32_e32 v154, 16, v193
	v_and_b32_e32 v155, 0xffff0000, v193
	v_sub_f32_e32 v152, v152, v154
	v_sub_f32_e32 v153, v153, v155
	v_cvt_pk_bf16_f32 v201, v152, v153
	v_mul_f32_e32 v150, v122, v168
	v_mul_f32_e32 v151, v123, v168
	v_fma_f32 v150, v16, v150, v24
	v_fma_f32 v151, v17, v151, v25
	v_mul_f32_e32 v152, v124, v168
	v_mul_f32_e32 v153, v125, v168
	v_fma_f32 v152, v18, v152, v26
	v_fma_f32 v153, v19, v153, v27
	v_cvt_pk_bf16_f32 v194, v150, v151
	v_cvt_pk_bf16_f32 v195, v152, v153
	v_lshlrev_b32_e32 v154, 16, v194
	v_and_b32_e32 v155, 0xffff0000, v194
	v_sub_f32_e32 v150, v150, v154
	v_sub_f32_e32 v151, v151, v155
	v_cvt_pk_bf16_f32 v202, v150, v151
	v_lshlrev_b32_e32 v154, 16, v195
	v_and_b32_e32 v155, 0xffff0000, v195
	v_sub_f32_e32 v152, v152, v154
	v_sub_f32_e32 v153, v153, v155
	v_cvt_pk_bf16_f32 v203, v152, v153
	v_mul_f32_e32 v150, v126, v168
	v_mul_f32_e32 v151, v127, v168
	v_fma_f32 v150, v20, v150, v28
	v_fma_f32 v151, v21, v151, v29
	v_mul_f32_e32 v152, v128, v168
	v_mul_f32_e32 v153, v129, v168
	v_fma_f32 v152, v22, v152, v30
	v_fma_f32 v153, v23, v153, v31
	v_cvt_pk_bf16_f32 v196, v150, v151
	v_cvt_pk_bf16_f32 v197, v152, v153
	v_lshlrev_b32_e32 v154, 16, v196
	v_and_b32_e32 v155, 0xffff0000, v196
	v_sub_f32_e32 v150, v150, v154
	v_sub_f32_e32 v151, v151, v155
	v_cvt_pk_bf16_f32 v204, v150, v151
	v_lshlrev_b32_e32 v154, 16, v197
	v_and_b32_e32 v155, 0xffff0000, v197
	v_sub_f32_e32 v152, v152, v154
	v_sub_f32_e32 v153, v153, v155
	v_cvt_pk_bf16_f32 v205, v152, v153
	global_store_dwordx2 v[184:185], v[190:191], off offset:0
	global_store_dwordx2 v[184:185], v[192:193], off offset:512
	global_store_dwordx2 v[184:185], v[194:195], off offset:1024
	global_store_dwordx2 v[184:185], v[196:197], off offset:1536
	global_store_dwordx2 v[186:187], v[198:199], off offset:0
	global_store_dwordx2 v[186:187], v[200:201], off offset:512
	global_store_dwordx2 v[186:187], v[202:203], off offset:1024
	global_store_dwordx2 v[186:187], v[204:205], off offset:1536
	s_add_i32 s98, s98, 2
	s_cmp_lt_u32 s98, 32
	s_cbranch_scc1 .Lmy_ln1r_loop
	s_waitcnt vmcnt(0)
	s_branch .LBB0_557

; __device__ __forceinline__ float bflo(unsigned u) { return __uint_as_float(u << 16); }
; __device__ __forceinline__ float bfhi(unsigned u) { return __uint_as_float(u & 0xffff0000u); }
; __device__ __forceinline__ void ln_panel(int pm, const float* resf, const bf16* rlo, const bf16* dlt, float* xo, const float* gam, const float* bet, bf16* xb, bf16* wlo, bool fin, float alpha) {
;     ...
; #pragma unroll 4
;     for (int r = wave * 32; r < wave * 32 + 32; ++r) {
;         const size_t grow = (size_t)(pm * 256 + r) * DM + 4 * lane, prow = (size_t)r * DM + 4 * lane;
;         f32x4 v[4]; float s = 0.f;
; #pragma unroll
;         for (int j = 0; j < 4; ++j) { f32x4 x; const u32x2 d = *(const u32x2*)(dlt + prow + 256 * j);
;             if (resf) x = *(const f32x4*)(resf + grow + 256 * j);
;             else { const u32x2 h = *(const u32x2*)(xb + grow + 256 * j), l = *(const u32x2*)(rlo + prow + 256 * j);
;                    x = (f32x4){bflo(h.x) + bflo(l.x), bfhi(h.x) + bfhi(l.x), bflo(h.y) + bflo(l.y), bfhi(h.y) + bfhi(l.y)}; }
;             v[j] = (f32x4){x.x * alpha + bflo(d.x), x.y * alpha + bfhi(d.x), x.z * alpha + bflo(d.y), x.w * alpha + bfhi(d.y)}; s += (v[j].x + v[j].y) + (v[j].z + v[j].w); }
;         const float mean = wave_sum(s) * (1.f / DM); float s2 = 0.f;
; #pragma unroll
;         for (int j = 0; j < 4; ++j) { v[j] = v[j] - mean; s2 += (v[j].x * v[j].x + v[j].y * v[j].y) + (v[j].z * v[j].z + v[j].w * v[j].w); }
;         const float rstd = 1.f / sqrtf(wave_sum(s2) * (1.f / DM) + LN_EPS);
.Lmy_ln2h_entry:
	v_lshlrev_b32_e32 v150, 16, v66
	v_and_b32_e32 v151, 0xffff0000, v66
	v_lshlrev_b32_e32 v152, 16, v74
	v_and_b32_e32 v153, 0xffff0000, v74
	v_add_f32_e32 v150, v150, v152
	v_add_f32_e32 v151, v151, v153
	v_lshlrev_b32_e32 v152, 16, v82
	v_and_b32_e32 v153, 0xffff0000, v82
	v_fma_f32 v114, v150, v164, v152
	v_fma_f32 v115, v151, v165, v153
	v_lshlrev_b32_e32 v150, 16, v67
	v_and_b32_e32 v151, 0xffff0000, v67
	v_lshlrev_b32_e32 v152, 16, v75
	v_and_b32_e32 v153, 0xffff0000, v75
	v_add_f32_e32 v150, v150, v152
	v_add_f32_e32 v151, v151, v153
	v_lshlrev_b32_e32 v152, 16, v83
	v_and_b32_e32 v153, 0xffff0000, v83
	v_fma_f32 v116, v150, v164, v152
	v_fma_f32 v117, v151, v165, v153
	v_lshlrev_b32_e32 v150, 16, v68
	v_and_b32_e32 v151, 0xffff0000, v68
	v_lshlrev_b32_e32 v152, 16, v76
	v_and_b32_e32 v153, 0xffff0000, v76
	v_add_f32_e32 v150, v150, v152
	v_add_f32_e32 v151, v151, v153
	v_lshlrev_b32_e32 v152, 16, v84
	v_and_b32_e32 v153, 0xffff0000, v84
	v_fma_f32 v118, v150, v164, v152
	v_fma_f32 v119, v151, v165, v153
	v_lshlrev_b32_e32 v150, 16, v69
	v_and_b32_e32 v151, 0xffff0000, v69
	v_lshlrev_b32_e32 v152, 16, v77
	v_and_b32_e32 v153, 0xffff0000, v77
	v_add_f32_e32 v150, v150, v152
	v_add_f32_e32 v151, v151, v153
	v_lshlrev_b32_e32 v152, 16, v85
	v_and_b32_e32 v153, 0xffff0000, v85
	v_fma_f32 v120, v150, v164, v152
	v_fma_f32 v121, v151, v165, v153
	v_lshlrev_b32_e32 v150, 16, v70
	v_and_b32_e32 v151, 0xffff0000, v70
	v_lshlrev_b32_e32 v152, 16, v78
	v_and_b32_e32 v153, 0xffff0000, v78
	v_add_f32_e32 v150, v150, v152
	v_add_f32_e32 v151, v151, v153
	v_lshlrev_b32_e32 v152, 16, v86
	v_and_b32_e32 v153, 0xffff0000, v86
	v_fma_f32 v122, v150, v164, v152
	v_fma_f32 v123, v151, v165, v153
	v_lshlrev_b32_e32 v150, 16, v71
	v_and_b32_e32 v151, 0xffff0000, v71
	v_lshlrev_b32_e32 v152, 16, v79
	v_and_b32_e32 v153, 0xffff0000, v79
	v_add_f32_e32 v150, v150, v152
	v_add_f32_e32 v151, v151, v153
	v_lshlrev_b32_e32 v152, 16, v87
	v_and_b32_e32 v153, 0xffff0000, v87
	v_fma_f32 v124, v150, v164, v152
	v_fma_f32 v125, v151, v165, v153
	v_lshlrev_b32_e32 v150, 16, v72
	v_and_b32_e32 v151, 0xffff0000, v72
	v_lshlrev_b32_e32 v152, 16, v80
	v_and_b32_e32 v153, 0xffff0000, v80
	v_add_f32_e32 v150, v150, v152
	v_add_f32_e32 v151, v151, v153
	v_lshlrev_b32_e32 v152, 16, v88
	v_and_b32_e32 v153, 0xffff0000, v88
	v_fma_f32 v126, v150, v164, v152
	v_fma_f32 v127, v151, v165, v153
	v_lshlrev_b32_e32 v150, 16, v73
	v_and_b32_e32 v151, 0xffff0000, v73
	v_lshlrev_b32_e32 v152, 16, v81
	v_and_b32_e32 v153, 0xffff0000, v81
	v_add_f32_e32 v150, v150, v152
	v_add_f32_e32 v151, v151, v153
	v_lshlrev_b32_e32 v152, 16, v89
	v_and_b32_e32 v153, 0xffff0000, v89
	v_fma_f32 v128, v150, v164, v152
	v_fma_f32 v129, v151, v165, v153
	s_add_i32 s0, s98, 2
	s_min_u32 s0, s0, 31
	s_lshl_b32 s0, s0, 11
	s_mov_b32 s1, 0
	v_lshl_add_u64 v[184:185], s[0:1], 0, v[178:179]
	v_lshl_add_u64 v[186:187], s[0:1], 0, v[172:173]
	v_lshl_add_u64 v[188:189], s[0:1], 0, v[176:177]
	global_load_dwordx2 v[82:83], v[184:185], off offset:-1024
	global_load_dwordx2 v[84:85], v[184:185], off offset:-512
	global_load_dwordx2 v[86:87], v[184:185], off offset:0
	global_load_dwordx2 v[88:89], v[184:185], off offset:512
	global_load_dwordx2 v[66:67], v[186:187], off offset:-1024
	global_load_dwordx2 v[68:69], v[186:187], off offset:-512
	global_load_dwordx2 v[70:71], v[186:187], off offset:0
	global_load_dwordx2 v[72:73], v[186:187], off offset:512
	global_load_dwordx2 v[74:75], v[188:189], off offset:-1024
	global_load_dwordx2 v[76:77], v[188:189], off offset:-512
	global_load_dwordx2 v[78:79], v[188:189], off offset:0
	global_load_dwordx2 v[80:81], v[188:189], off offset:512
	v_add_f32_e32 v154, v114, v116
	v_add_f32_e32 v155, v115, v117
	v_add_f32_e32 v156, v118, v120
	v_add_f32_e32 v157, v119, v121
	v_add_f32_e32 v154, v154, v156
	v_add_f32_e32 v155, v155, v157
	v_add_f32_e32 v156, v122, v124
	v_add_f32_e32 v157, v123, v125
	v_add_f32_e32 v154, v154, v156
	v_add_f32_e32 v155, v155, v157
	v_add_f32_e32 v156, v126, v128
	v_add_f32_e32 v157, v127, v129
	v_add_f32_e32 v154, v154, v156
	v_add_f32_e32 v155, v155, v157
	v_add_f32_e32 v154, v154, v155
	s_nop 1
	v_add_f32_dpp v160, v154, v154 quad_perm:[1,0,3,2] row_mask:0xf bank_mask:0xf
	s_nop 1
	v_add_f32_dpp v160, v160, v160 quad_perm:[2,3,0,1] row_mask:0xf bank_mask:0xf
	s_nop 1
	v_add_f32_dpp v160, v160, v160 row_half_mirror row_mask:0xf bank_mask:0xf
	s_nop 1
	v_add_f32_dpp v160, v160, v160 row_mirror row_mask:0xf bank_mask:0xf
	s_nop 1
	v_add_f32_dpp v160, v160, v160 row_bcast:15 row_mask:0xa bank_mask:0xf
	s_nop 1
	v_add_f32_dpp v160, v160, v160 row_bcast:31 row_mask:0xc bank_mask:0xf
	s_nop 1
	v_readlane_b32 s0, v160, 63
	s_nop 2
	v_mov_b32_e32 v170, s0
	v_mul_f32_e32 v156, 0xba800000, v170
	v_mul_f32_e32 v157, 0xba800000, v170
	v_add_f32_e32 v114, v114, v156
	v_add_f32_e32 v115, v115, v157
	v_add_f32_e32 v116, v116, v156
	v_add_f32_e32 v117, v117, v157
	v_add_f32_e32 v118, v118, v156
	v_add_f32_e32 v119, v119, v157
	v_add_f32_e32 v120, v120, v156
	v_add_f32_e32 v121, v121, v157
	v_add_f32_e32 v122, v122, v156
	v_add_f32_e32 v123, v123, v157
	v_add_f32_e32 v124, v124, v156
	v_add_f32_e32 v125, v125, v157
	v_add_f32_e32 v126, v126, v156
	v_add_f32_e32 v127, v127, v157
	v_add_f32_e32 v128, v128, v156
	v_add_f32_e32 v129, v129, v157
	v_mul_f32_e32 v154, v114, v114
	v_mul_f32_e32 v155, v115, v115
	v_fma_f32 v154, v116, v116, v154
	v_fma_f32 v155, v117, v117, v155
	v_fma_f32 v154, v118, v118, v154
	v_fma_f32 v155, v119, v119, v155
	v_fma_f32 v154, v120, v120, v154
	v_fma_f32 v155, v121, v121, v155
	v_fma_f32 v154, v122, v122, v154
; __device__ __forceinline__ unsigned pk2(float lo, float hi) { return pg8::cvt_pk_bf16(lo, hi); }
; __device__ __forceinline__ float bflo(unsigned u) { return __uint_as_float(u << 16); }
; __device__ __forceinline__ float bfhi(unsigned u) { return __uint_as_float(u & 0xffff0000u); }
; __device__ __forceinline__ void ln_panel(int pm, const float* resf, const bf16* rlo, const bf16* dlt, float* xo, const float* gam, const float* bet, bf16* xb, bf16* wlo, bool fin, float alpha) {
;     ...
; #pragma unroll
;         for (int j = 0; j < 4; ++j) { v[j] = v[j] - mean; s2 += (v[j].x * v[j].x + v[j].y * v[j].y) + (v[j].z * v[j].z + v[j].w * v[j].w); }
;         const float rstd = 1.f / sqrtf(wave_sum(s2) * (1.f / DM) + LN_EPS);
; #pragma unroll
;         for (int j = 0; j < 4; ++j) { const f32x4 o = v[j] * rstd * gv[j] + bv[j];
;             if (fin) *(f32x4*)(xo + grow + 256 * j) = o;
;             else { u32x2 w; w.x = pk2(o.x, o.y); w.y = pk2(o.z, o.w); *(u32x2*)(xb + grow + 256 * j) = w;
;                    u32x2 q; q.x = pk2(o.x - bflo(w.x), o.y - bfhi(w.x)); q.y = pk2(o.z - bflo(w.y), o.w - bfhi(w.y)); *(u32x2*)(wlo + prow + 256 * j) = q; } }
	v_fma_f32 v155, v123, v123, v155
	v_fma_f32 v154, v124, v124, v154
	v_fma_f32 v155, v125, v125, v155
	v_fma_f32 v154, v126, v126, v154
	v_fma_f32 v155, v127, v127, v155
	v_fma_f32 v154, v128, v128, v154
	v_fma_f32 v155, v129, v129, v155
	v_add_f32_e32 v154, v154, v155
	s_nop 1
	v_add_f32_dpp v160, v154, v154 quad_perm:[1,0,3,2] row_mask:0xf bank_mask:0xf
	s_nop 1
	v_add_f32_dpp v160, v160, v160 quad_perm:[2,3,0,1] row_mask:0xf bank_mask:0xf
	s_nop 1
	v_add_f32_dpp v160, v160, v160 row_half_mirror row_mask:0xf bank_mask:0xf
	s_nop 1
	v_add_f32_dpp v160, v160, v160 row_mirror row_mask:0xf bank_mask:0xf
	s_nop 1
	v_add_f32_dpp v160, v160, v160 row_bcast:15 row_mask:0xa bank_mask:0xf
	s_nop 1
	v_add_f32_dpp v160, v160, v160 row_bcast:31 row_mask:0xc bank_mask:0xf
	s_nop 1
	v_readlane_b32 s0, v160, 63
	s_nop 2
	v_mov_b32_e32 v170, s0
	v_fmamk_f32 v154, v170, 0x3a800000, v166
	s_mov_b32 s0, 0xf800000
	v_mul_f32_e32 v155, 0x4f800000, v154
	v_cmp_gt_f32_e32 vcc, s0, v154
	s_nop 1
	v_cndmask_b32_e32 v154, v154, v155, vcc
	v_sqrt_f32_e32 v155, v154
	s_nop 0
	v_add_u32_e32 v156, -1, v155
	v_fma_f32 v157, -v156, v155, v154
	v_cmp_ge_f32_e64 s[0:1], 0, v157
	v_add_u32_e32 v157, 1, v155
	s_nop 0
	v_cndmask_b32_e64 v156, v155, v156, s[0:1]
	v_fma_f32 v155, -v157, v155, v154
	v_cmp_lt_f32_e64 s[0:1], 0, v155
	s_nop 1
	v_cndmask_b32_e64 v155, v156, v157, s[0:1]
	v_mul_f32_e32 v156, 0x37800000, v155
	v_cndmask_b32_e32 v155, v155, v156, vcc
	v_cmp_class_f32_e32 vcc, v154, v167
	s_nop 1
	v_cndmask_b32_e32 v154, v155, v154, vcc
	v_div_scale_f32 v155, s[0:1], v154, v154, 1.0
	v_rcp_f32_e32 v156, v155
	s_nop 0
	v_fma_f32 v157, -v155, v156, 1.0
	v_fmac_f32_e32 v156, v157, v156
	v_div_scale_f32 v157, vcc, 1.0, v154, 1.0
	v_mul_f32_e32 v158, v157, v156
	v_fma_f32 v159, -v155, v158, v157
	v_fmac_f32_e32 v158, v159, v156
	v_fma_f32 v155, -v155, v158, v157
	s_nop 0
	v_div_fmas_f32 v155, v155, v156, v158
	v_div_fixup_f32 v168, v155, v154, 1.0
	s_add_i32 s0, s98, 0
	s_lshl_b32 s0, s0, 11
	s_mov_b32 s1, 0
	v_lshl_add_u64 v[184:185], s[0:1], 0, v[172:173]
	v_lshl_add_u64 v[186:187], s[0:1], 0, v[180:181]
	v_mul_f32_e32 v150, v114, v168
	v_mul_f32_e32 v151, v115, v168
	v_fma_f32 v150, v0, v150, v8
	v_fma_f32 v151, v1, v151, v9
	v_mul_f32_e32 v152, v116, v168
	v_mul_f32_e32 v153, v117, v168
	v_fma_f32 v152, v2, v152, v10
	v_fma_f32 v153, v3, v153, v11
	v_cvt_pk_bf16_f32 v190, v150, v151
	v_cvt_pk_bf16_f32 v191, v152, v153
	v_lshlrev_b32_e32 v154, 16, v190
	v_and_b32_e32 v155, 0xffff0000, v190
	v_sub_f32_e32 v150, v150, v154
	v_sub_f32_e32 v151, v151, v155
	v_cvt_pk_bf16_f32 v198, v150, v151
	v_lshlrev_b32_e32 v154, 16, v191
	v_and_b32_e32 v155, 0xffff0000, v191
	v_sub_f32_e32 v152, v152, v154
	v_sub_f32_e32 v153, v153, v155
	v_cvt_pk_bf16_f32 v199, v152, v153
	v_mul_f32_e32 v150, v118, v168
	v_mul_f32_e32 v151, v119, v168
	v_fma_f32 v150, v4, v150, v12
	v_fma_f32 v151, v5, v151, v13
	v_mul_f32_e32 v152, v120, v168
	v_mul_f32_e32 v153, v121, v168
	v_fma_f32 v152, v6, v152, v14
	v_fma_f32 v153, v7, v153, v15
	v_cvt_pk_bf16_f32 v192, v150, v151
	v_cvt_pk_bf16_f32 v193, v152, v153
	v_lshlrev_b32_e32 v154, 16, v192
	v_and_b32_e32 v155, 0xffff0000, v192
	v_sub_f32_e32 v150, v150, v154
	v_sub_f32_e32 v151, v151, v155
	v_cvt_pk_bf16_f32 v200, v150, v151
	v_lshlrev_b32_e32 v154, 16, v193
	v_and_b32_e32 v155, 0xffff0000, v193
	v_sub_f32_e32 v152, v152, v154
	v_sub_f32_e32 v153, v153, v155
	v_cvt_pk_bf16_f32 v201, v152, v153
	v_mul_f32_e32 v150, v122, v168
	v_mul_f32_e32 v151, v123, v168
	v_fma_f32 v150, v16, v150, v24
	v_fma_f32 v151, v17, v151, v25
	v_mul_f32_e32 v152, v124, v168
	v_mul_f32_e32 v153, v125, v168
	v_fma_f32 v152, v18, v152, v26
	v_fma_f32 v153, v19, v153, v27
	v_cvt_pk_bf16_f32 v194, v150, v151
	v_cvt_pk_bf16_f32 v195, v152, v153
	v_lshlrev_b32_e32 v154, 16, v194
	v_and_b32_e32 v155, 0xffff0000, v194
	v_sub_f32_e32 v150, v150, v154
	v_sub_f32_e32 v151, v151, v155
	v_cvt_pk_bf16_f32 v202, v150, v151
	v_lshlrev_b32_e32 v154, 16, v195
	v_and_b32_e32 v155, 0xffff0000, v195
	v_sub_f32_e32 v152, v152, v154
	v_sub_f32_e32 v153, v153, v155
	v_cvt_pk_bf16_f32 v203, v152, v153
	v_mul_f32_e32 v150, v126, v168
	v_mul_f32_e32 v151, v127, v168
	v_fma_f32 v150, v20, v150, v28
	v_fma_f32 v151, v21, v151, v29
	v_mul_f32_e32 v152, v128, v168
	v_mul_f32_e32 v153, v129, v168
	v_fma_f32 v152, v22, v152, v30
	v_fma_f32 v153, v23, v153, v31
	v_cvt_pk_bf16_f32 v196, v150, v151
	v_cvt_pk_bf16_f32 v197, v152, v153
	v_lshlrev_b32_e32 v154, 16, v196
	v_and_b32_e32 v155, 0xffff0000, v196
	v_sub_f32_e32 v150, v150, v154
	v_sub_f32_e32 v151, v151, v155
	v_cvt_pk_bf16_f32 v204, v150, v151
	v_lshlrev_b32_e32 v154, 16, v197
	v_and_b32_e32 v155, 0xffff0000, v197
	v_sub_f32_e32 v152, v152, v154
	v_sub_f32_e32 v153, v153, v155
	v_cvt_pk_bf16_f32 v205, v152, v153
	global_store_dwordx2 v[184:185], v[190:191], off offset:-1024
	global_store_dwordx2 v[184:185], v[192:193], off offset:-512
	global_store_dwordx2 v[184:185], v[194:195], off offset:0
	global_store_dwordx2 v[184:185], v[196:197], off offset:512
	global_store_dwordx2 v[186:187], v[198:199], off offset:0
	global_store_dwordx2 v[186:187], v[200:201], off offset:512
	global_store_dwordx2 v[186:187], v[202:203], off offset:1024
	global_store_dwordx2 v[186:187], v[204:205], off offset:1536
	s_waitcnt vmcnt(20)
; __device__ __forceinline__ float bflo(unsigned u) { return __uint_as_float(u << 16); }
; __device__ __forceinline__ float bfhi(unsigned u) { return __uint_as_float(u & 0xffff0000u); }
; __device__ __forceinline__ void ln_panel(int pm, const float* resf, const bf16* rlo, const bf16* dlt, float* xo, const float* gam, const float* bet, bf16* xb, bf16* wlo, bool fin, float alpha) {
;     ...
;         for (int j = 0; j < 4; ++j) { f32x4 x; const u32x2 d = *(const u32x2*)(dlt + prow + 256 * j);
;             if (resf) x = *(const f32x4*)(resf + grow + 256 * j);
;             else { const u32x2 h = *(const u32x2*)(xb + grow + 256 * j), l = *(const u32x2*)(rlo + prow + 256 * j);
;                    x = (f32x4){bflo(h.x) + bflo(l.x), bfhi(h.x) + bfhi(l.x), bflo(h.y) + bflo(l.y), bfhi(h.y) + bfhi(l.y)}; }
;             v[j] = (f32x4){x.x * alpha + bflo(d.x), x.y * alpha + bfhi(d.x), x.z * alpha + bflo(d.y), x.w * alpha + bfhi(d.y)}; s += (v[j].x + v[j].y) + (v[j].z + v[j].w); }
;         const float mean = wave_sum(s) * (1.f / DM); float s2 = 0.f;
	v_lshlrev_b32_e32 v150, 16, v90
	v_and_b32_e32 v151, 0xffff0000, v90
	v_lshlrev_b32_e32 v152, 16, v98
	v_and_b32_e32 v153, 0xffff0000, v98
	v_add_f32_e32 v150, v150, v152
	v_add_f32_e32 v151, v151, v153
	v_lshlrev_b32_e32 v152, 16, v106
	v_and_b32_e32 v153, 0xffff0000, v106
	v_fma_f32 v114, v150, v164, v152
	v_fma_f32 v115, v151, v165, v153
	v_lshlrev_b32_e32 v150, 16, v91
	v_and_b32_e32 v151, 0xffff0000, v91
	v_lshlrev_b32_e32 v152, 16, v99
	v_and_b32_e32 v153, 0xffff0000, v99
	v_add_f32_e32 v150, v150, v152
	v_add_f32_e32 v151, v151, v153
	v_lshlrev_b32_e32 v152, 16, v107
	v_and_b32_e32 v153, 0xffff0000, v107
	v_fma_f32 v116, v150, v164, v152
	v_fma_f32 v117, v151, v165, v153
	v_lshlrev_b32_e32 v150, 16, v92
	v_and_b32_e32 v151, 0xffff0000, v92
	v_lshlrev_b32_e32 v152, 16, v100
	v_and_b32_e32 v153, 0xffff0000, v100
	v_add_f32_e32 v150, v150, v152
	v_add_f32_e32 v151, v151, v153
	v_lshlrev_b32_e32 v152, 16, v108
	v_and_b32_e32 v153, 0xffff0000, v108
	v_fma_f32 v118, v150, v164, v152
	v_fma_f32 v119, v151, v165, v153
	v_lshlrev_b32_e32 v150, 16, v93
	v_and_b32_e32 v151, 0xffff0000, v93
	v_lshlrev_b32_e32 v152, 16, v101
	v_and_b32_e32 v153, 0xffff0000, v101
	v_add_f32_e32 v150, v150, v152
	v_add_f32_e32 v151, v151, v153
	v_lshlrev_b32_e32 v152, 16, v109
	v_and_b32_e32 v153, 0xffff0000, v109
	v_fma_f32 v120, v150, v164, v152
	v_fma_f32 v121, v151, v165, v153
	v_lshlrev_b32_e32 v150, 16, v94
	v_and_b32_e32 v151, 0xffff0000, v94
	v_lshlrev_b32_e32 v152, 16, v102
	v_and_b32_e32 v153, 0xffff0000, v102
	v_add_f32_e32 v150, v150, v152
	v_add_f32_e32 v151, v151, v153
	v_lshlrev_b32_e32 v152, 16, v110
	v_and_b32_e32 v153, 0xffff0000, v110
	v_fma_f32 v122, v150, v164, v152
	v_fma_f32 v123, v151, v165, v153
	v_lshlrev_b32_e32 v150, 16, v95
	v_and_b32_e32 v151, 0xffff0000, v95
	v_lshlrev_b32_e32 v152, 16, v103
	v_and_b32_e32 v153, 0xffff0000, v103
	v_add_f32_e32 v150, v150, v152
	v_add_f32_e32 v151, v151, v153
	v_lshlrev_b32_e32 v152, 16, v111
	v_and_b32_e32 v153, 0xffff0000, v111
	v_fma_f32 v124, v150, v164, v152
	v_fma_f32 v125, v151, v165, v153
	v_lshlrev_b32_e32 v150, 16, v96
	v_and_b32_e32 v151, 0xffff0000, v96
	v_lshlrev_b32_e32 v152, 16, v104
	v_and_b32_e32 v153, 0xffff0000, v104
	v_add_f32_e32 v150, v150, v152
	v_add_f32_e32 v151, v151, v153
	v_lshlrev_b32_e32 v152, 16, v112
	v_and_b32_e32 v153, 0xffff0000, v112
	v_fma_f32 v126, v150, v164, v152
	v_fma_f32 v127, v151, v165, v153
	v_lshlrev_b32_e32 v150, 16, v97
	v_and_b32_e32 v151, 0xffff0000, v97
	v_lshlrev_b32_e32 v152, 16, v105
	v_and_b32_e32 v153, 0xffff0000, v105
	v_add_f32_e32 v150, v150, v152
	v_add_f32_e32 v151, v151, v153
	v_lshlrev_b32_e32 v152, 16, v113
	v_and_b32_e32 v153, 0xffff0000, v113
	v_fma_f32 v128, v150, v164, v152
	v_fma_f32 v129, v151, v165, v153
	s_add_i32 s0, s98, 3
	s_min_u32 s0, s0, 31
	s_lshl_b32 s0, s0, 11
	s_mov_b32 s1, 0
	v_lshl_add_u64 v[184:185], s[0:1], 0, v[178:179]
	v_lshl_add_u64 v[186:187], s[0:1], 0, v[172:173]
	v_lshl_add_u64 v[188:189], s[0:1], 0, v[176:177]
	global_load_dwordx2 v[106:107], v[184:185], off offset:-1024
	global_load_dwordx2 v[108:109], v[184:185], off offset:-512
	global_load_dwordx2 v[110:111], v[184:185], off offset:0
	global_load_dwordx2 v[112:113], v[184:185], off offset:512
	global_load_dwordx2 v[90:91], v[186:187], off offset:-1024
	global_load_dwordx2 v[92:93], v[186:187], off offset:-512
	global_load_dwordx2 v[94:95], v[186:187], off offset:0
	global_load_dwordx2 v[96:97], v[186:187], off offset:512
	global_load_dwordx2 v[98:99], v[188:189], off offset:-1024
	global_load_dwordx2 v[100:101], v[188:189], off offset:-512
	global_load_dwordx2 v[102:103], v[188:189], off offset:0
	global_load_dwordx2 v[104:105], v[188:189], off offset:512
	v_add_f32_e32 v154, v114, v116
	v_add_f32_e32 v155, v115, v117
	v_add_f32_e32 v156, v118, v120
	v_add_f32_e32 v157, v119, v121
	v_add_f32_e32 v154, v154, v156
	v_add_f32_e32 v155, v155, v157
	v_add_f32_e32 v156, v122, v124
	v_add_f32_e32 v157, v123, v125
	v_add_f32_e32 v154, v154, v156
	v_add_f32_e32 v155, v155, v157
	v_add_f32_e32 v156, v126, v128
	v_add_f32_e32 v157, v127, v129
	v_add_f32_e32 v154, v154, v156
	v_add_f32_e32 v155, v155, v157
	v_add_f32_e32 v154, v154, v155
	s_nop 1
	v_add_f32_dpp v160, v154, v154 quad_perm:[1,0,3,2] row_mask:0xf bank_mask:0xf
	s_nop 1
	v_add_f32_dpp v160, v160, v160 quad_perm:[2,3,0,1] row_mask:0xf bank_mask:0xf
	s_nop 1
	v_add_f32_dpp v160, v160, v160 row_half_mirror row_mask:0xf bank_mask:0xf
	s_nop 1
	v_add_f32_dpp v160, v160, v160 row_mirror row_mask:0xf bank_mask:0xf
	s_nop 1
	v_add_f32_dpp v160, v160, v160 row_bcast:15 row_mask:0xa bank_mask:0xf
	s_nop 1
	v_add_f32_dpp v160, v160, v160 row_bcast:31 row_mask:0xc bank_mask:0xf
	s_nop 1
	v_readlane_b32 s0, v160, 63
	s_nop 2
	v_mov_b32_e32 v170, s0
	v_mul_f32_e32 v156, 0xba800000, v170
	v_mul_f32_e32 v157, 0xba800000, v170
	v_add_f32_e32 v114, v114, v156
	v_add_f32_e32 v115, v115, v157
	v_add_f32_e32 v116, v116, v156
	v_add_f32_e32 v117, v117, v157
	v_add_f32_e32 v118, v118, v156
	v_add_f32_e32 v119, v119, v157
	v_add_f32_e32 v120, v120, v156
	v_add_f32_e32 v121, v121, v157
	v_add_f32_e32 v122, v122, v156
	v_add_f32_e32 v123, v123, v157
	v_add_f32_e32 v124, v124, v156
	v_add_f32_e32 v125, v125, v157
	v_add_f32_e32 v126, v126, v156
	v_add_f32_e32 v127, v127, v157
	v_add_f32_e32 v128, v128, v156
	v_add_f32_e32 v129, v129, v157
	v_mul_f32_e32 v154, v114, v114
	v_mul_f32_e32 v155, v115, v115
	v_fma_f32 v154, v116, v116, v154
	v_fma_f32 v155, v117, v117, v155
	v_fma_f32 v154, v118, v118, v154
; __device__ __forceinline__ unsigned pk2(float lo, float hi) { return pg8::cvt_pk_bf16(lo, hi); }
; __device__ __forceinline__ float bflo(unsigned u) { return __uint_as_float(u << 16); }
; __device__ __forceinline__ float bfhi(unsigned u) { return __uint_as_float(u & 0xffff0000u); }
; __device__ __forceinline__ void ln_panel(int pm, const float* resf, const bf16* rlo, const bf16* dlt, float* xo, const float* gam, const float* bet, bf16* xb, bf16* wlo, bool fin, float alpha) {
;     ...
; #pragma unroll
;         for (int j = 0; j < 4; ++j) { v[j] = v[j] - mean; s2 += (v[j].x * v[j].x + v[j].y * v[j].y) + (v[j].z * v[j].z + v[j].w * v[j].w); }
;         const float rstd = 1.f / sqrtf(wave_sum(s2) * (1.f / DM) + LN_EPS);
; #pragma unroll
;         for (int j = 0; j < 4; ++j) { const f32x4 o = v[j] * rstd * gv[j] + bv[j];
;             if (fin) *(f32x4*)(xo + grow + 256 * j) = o;
;             else { u32x2 w; w.x = pk2(o.x, o.y); w.y = pk2(o.z, o.w); *(u32x2*)(xb + grow + 256 * j) = w;
;                    u32x2 q; q.x = pk2(o.x - bflo(w.x), o.y - bfhi(w.x)); q.y = pk2(o.z - bflo(w.y), o.w - bfhi(w.y)); *(u32x2*)(wlo + prow + 256 * j) = q; } }
	v_fma_f32 v155, v119, v119, v155
	v_fma_f32 v154, v120, v120, v154
	v_fma_f32 v155, v121, v121, v155
	v_fma_f32 v154, v122, v122, v154
	v_fma_f32 v155, v123, v123, v155
	v_fma_f32 v154, v124, v124, v154
	v_fma_f32 v155, v125, v125, v155
	v_fma_f32 v154, v126, v126, v154
	v_fma_f32 v155, v127, v127, v155
	v_fma_f32 v154, v128, v128, v154
	v_fma_f32 v155, v129, v129, v155
	v_add_f32_e32 v154, v154, v155
	s_nop 1
	v_add_f32_dpp v160, v154, v154 quad_perm:[1,0,3,2] row_mask:0xf bank_mask:0xf
	s_nop 1
	v_add_f32_dpp v160, v160, v160 quad_perm:[2,3,0,1] row_mask:0xf bank_mask:0xf
	s_nop 1
	v_add_f32_dpp v160, v160, v160 row_half_mirror row_mask:0xf bank_mask:0xf
	s_nop 1
	v_add_f32_dpp v160, v160, v160 row_mirror row_mask:0xf bank_mask:0xf
	s_nop 1
	v_add_f32_dpp v160, v160, v160 row_bcast:15 row_mask:0xa bank_mask:0xf
	s_nop 1
	v_add_f32_dpp v160, v160, v160 row_bcast:31 row_mask:0xc bank_mask:0xf
	s_nop 1
	v_readlane_b32 s0, v160, 63
	s_nop 2
	v_mov_b32_e32 v170, s0
	v_fmamk_f32 v154, v170, 0x3a800000, v166
	s_mov_b32 s0, 0xf800000
	v_mul_f32_e32 v155, 0x4f800000, v154
	v_cmp_gt_f32_e32 vcc, s0, v154
	s_nop 1
	v_cndmask_b32_e32 v154, v154, v155, vcc
	v_sqrt_f32_e32 v155, v154
	s_nop 0
	v_add_u32_e32 v156, -1, v155
	v_fma_f32 v157, -v156, v155, v154
	v_cmp_ge_f32_e64 s[0:1], 0, v157
	v_add_u32_e32 v157, 1, v155
	s_nop 0
	v_cndmask_b32_e64 v156, v155, v156, s[0:1]
	v_fma_f32 v155, -v157, v155, v154
	v_cmp_lt_f32_e64 s[0:1], 0, v155
	s_nop 1
	v_cndmask_b32_e64 v155, v156, v157, s[0:1]
	v_mul_f32_e32 v156, 0x37800000, v155
	v_cndmask_b32_e32 v155, v155, v156, vcc
	v_cmp_class_f32_e32 vcc, v154, v167
	s_nop 1
	v_cndmask_b32_e32 v154, v155, v154, vcc
	v_div_scale_f32 v155, s[0:1], v154, v154, 1.0
	v_rcp_f32_e32 v156, v155
	s_nop 0
	v_fma_f32 v157, -v155, v156, 1.0
	v_fmac_f32_e32 v156, v157, v156
	v_div_scale_f32 v157, vcc, 1.0, v154, 1.0
	v_mul_f32_e32 v158, v157, v156
	v_fma_f32 v159, -v155, v158, v157
	v_fmac_f32_e32 v158, v159, v156
	v_fma_f32 v155, -v155, v158, v157
	s_nop 0
	v_div_fmas_f32 v155, v155, v156, v158
	v_div_fixup_f32 v168, v155, v154, 1.0
	s_add_i32 s0, s98, 1
	s_lshl_b32 s0, s0, 11
	s_mov_b32 s1, 0
	v_lshl_add_u64 v[184:185], s[0:1], 0, v[172:173]
	v_lshl_add_u64 v[186:187], s[0:1], 0, v[180:181]
	v_mul_f32_e32 v150, v114, v168
	v_mul_f32_e32 v151, v115, v168
	v_fma_f32 v150, v0, v150, v8
	v_fma_f32 v151, v1, v151, v9
	v_mul_f32_e32 v152, v116, v168
	v_mul_f32_e32 v153, v117, v168
	v_fma_f32 v152, v2, v152, v10
	v_fma_f32 v153, v3, v153, v11
	v_cvt_pk_bf16_f32 v190, v150, v151
	v_cvt_pk_bf16_f32 v191, v152, v153
	v_lshlrev_b32_e32 v154, 16, v190
	v_and_b32_e32 v155, 0xffff0000, v190
	v_sub_f32_e32 v150, v150, v154
	v_sub_f32_e32 v151, v151, v155
	v_cvt_pk_bf16_f32 v198, v150, v151
	v_lshlrev_b32_e32 v154, 16, v191
	v_and_b32_e32 v155, 0xffff0000, v191
	v_sub_f32_e32 v152, v152, v154
	v_sub_f32_e32 v153, v153, v155
	v_cvt_pk_bf16_f32 v199, v152, v153
	v_mul_f32_e32 v150, v118, v168
	v_mul_f32_e32 v151, v119, v168
	v_fma_f32 v150, v4, v150, v12
	v_fma_f32 v151, v5, v151, v13
	v_mul_f32_e32 v152, v120, v168
	v_mul_f32_e32 v153, v121, v168
	v_fma_f32 v152, v6, v152, v14
	v_fma_f32 v153, v7, v153, v15
	v_cvt_pk_bf16_f32 v192, v150, v151
	v_cvt_pk_bf16_f32 v193, v152, v153
	v_lshlrev_b32_e32 v154, 16, v192
	v_and_b32_e32 v155, 0xffff0000, v192
	v_sub_f32_e32 v150, v150, v154
	v_sub_f32_e32 v151, v151, v155
	v_cvt_pk_bf16_f32 v200, v150, v151
	v_lshlrev_b32_e32 v154, 16, v193
	v_and_b32_e32 v155, 0xffff0000, v193
	v_sub_f32_e32 v152, v152, v154
	v_sub_f32_e32 v153, v153, v155
	v_cvt_pk_bf16_f32 v201, v152, v153
	v_mul_f32_e32 v150, v122, v168
	v_mul_f32_e32 v151, v123, v168
	v_fma_f32 v150, v16, v150, v24
	v_fma_f32 v151, v17, v151, v25
	v_mul_f32_e32 v152, v124, v168
	v_mul_f32_e32 v153, v125, v168
	v_fma_f32 v152, v18, v152, v26
	v_fma_f32 v153, v19, v153, v27
	v_cvt_pk_bf16_f32 v194, v150, v151
	v_cvt_pk_bf16_f32 v195, v152, v153
	v_lshlrev_b32_e32 v154, 16, v194
	v_and_b32_e32 v155, 0xffff0000, v194
	v_sub_f32_e32 v150, v150, v154
	v_sub_f32_e32 v151, v151, v155
	v_cvt_pk_bf16_f32 v202, v150, v151
	v_lshlrev_b32_e32 v154, 16, v195
	v_and_b32_e32 v155, 0xffff0000, v195
	v_sub_f32_e32 v152, v152, v154
	v_sub_f32_e32 v153, v153, v155
	v_cvt_pk_bf16_f32 v203, v152, v153
	v_mul_f32_e32 v150, v126, v168
	v_mul_f32_e32 v151, v127, v168
	v_fma_f32 v150, v20, v150, v28
	v_fma_f32 v151, v21, v151, v29
	v_mul_f32_e32 v152, v128, v168
	v_mul_f32_e32 v153, v129, v168
	v_fma_f32 v152, v22, v152, v30
	v_fma_f32 v153, v23, v153, v31
	v_cvt_pk_bf16_f32 v196, v150, v151
	v_cvt_pk_bf16_f32 v197, v152, v153
	v_lshlrev_b32_e32 v154, 16, v196
	v_and_b32_e32 v155, 0xffff0000, v196
	v_sub_f32_e32 v150, v150, v154
	v_sub_f32_e32 v151, v151, v155
	v_cvt_pk_bf16_f32 v204, v150, v151
	v_lshlrev_b32_e32 v154, 16, v197
	v_and_b32_e32 v155, 0xffff0000, v197
	v_sub_f32_e32 v152, v152, v154
	v_sub_f32_e32 v153, v153, v155
	v_cvt_pk_bf16_f32 v205, v152, v153
	global_store_dwordx2 v[184:185], v[190:191], off offset:-1024
	global_store_dwordx2 v[184:185], v[192:193], off offset:-512
	global_store_dwordx2 v[184:185], v[194:195], off offset:0
	global_store_dwordx2 v[184:185], v[196:197], off offset:512
	global_store_dwordx2 v[186:187], v[198:199], off offset:0
	global_store_dwordx2 v[186:187], v[200:201], off offset:512
	global_store_dwordx2 v[186:187], v[202:203], off offset:1024
	global_store_dwordx2 v[186:187], v[204:205], off offset:1536
	s_add_i32 s98, s98, 2
	s_cmp_lt_u32 s98, 32
	s_cbranch_scc1 .Lmy_ln2h_loop
	s_waitcnt vmcnt(0)
	s_branch .LBB0_467

; __device__ __forceinline__ float bflo(unsigned u) { return __uint_as_float(u << 16); }
; __device__ __forceinline__ float bfhi(unsigned u) { return __uint_as_float(u & 0xffff0000u); }
; __device__ __forceinline__ void ln_panel(int pm, const float* resf, const bf16* rlo, const bf16* dlt, float* xo, const float* gam, const float* bet, bf16* xb, bf16* wlo, bool fin, float alpha) {
;     ...
; #pragma unroll 4
;     for (int r = wave * 32; r < wave * 32 + 32; ++r) {
;         const size_t grow = (size_t)(pm * 256 + r) * DM + 4 * lane, prow = (size_t)r * DM + 4 * lane;
;         f32x4 v[4]; float s = 0.f;
; #pragma unroll
;         for (int j = 0; j < 4; ++j) { f32x4 x; const u32x2 d = *(const u32x2*)(dlt + prow + 256 * j);
;             if (resf) x = *(const f32x4*)(resf + grow + 256 * j);
;             else { const u32x2 h = *(const u32x2*)(xb + grow + 256 * j), l = *(const u32x2*)(rlo + prow + 256 * j);
;                    x = (f32x4){bflo(h.x) + bflo(l.x), bfhi(h.x) + bfhi(l.x), bflo(h.y) + bflo(l.y), bfhi(h.y) + bfhi(l.y)}; }
;             v[j] = (f32x4){x.x * alpha + bflo(d.x), x.y * alpha + bfhi(d.x), x.z * alpha + bflo(d.y), x.w * alpha + bfhi(d.y)}; s += (v[j].x + v[j].y) + (v[j].z + v[j].w); }
;         const float mean = wave_sum(s) * (1.f / DM); float s2 = 0.f;
; #pragma unroll
;         for (int j = 0; j < 4; ++j) { v[j] = v[j] - mean; s2 += (v[j].x * v[j].x + v[j].y * v[j].y) + (v[j].z * v[j].z + v[j].w * v[j].w); }
;         const float rstd = 1.f / sqrtf(wave_sum(s2) * (1.f / DM) + LN_EPS);
.Lmy_ln2f_entry:
	v_lshlrev_b32_e32 v150, 16, v66
	v_and_b32_e32 v151, 0xffff0000, v66
	v_lshlrev_b32_e32 v152, 16, v74
	v_and_b32_e32 v153, 0xffff0000, v74
	v_add_f32_e32 v150, v150, v152
	v_add_f32_e32 v151, v151, v153
	v_lshlrev_b32_e32 v152, 16, v82
	v_and_b32_e32 v153, 0xffff0000, v82
	v_fma_f32 v114, v150, v164, v152
	v_fma_f32 v115, v151, v165, v153
	v_lshlrev_b32_e32 v150, 16, v67
	v_and_b32_e32 v151, 0xffff0000, v67
	v_lshlrev_b32_e32 v152, 16, v75
	v_and_b32_e32 v153, 0xffff0000, v75
	v_add_f32_e32 v150, v150, v152
	v_add_f32_e32 v151, v151, v153
	v_lshlrev_b32_e32 v152, 16, v83
	v_and_b32_e32 v153, 0xffff0000, v83
	v_fma_f32 v116, v150, v164, v152
	v_fma_f32 v117, v151, v165, v153
	v_lshlrev_b32_e32 v150, 16, v68
	v_and_b32_e32 v151, 0xffff0000, v68
	v_lshlrev_b32_e32 v152, 16, v76
	v_and_b32_e32 v153, 0xffff0000, v76
	v_add_f32_e32 v150, v150, v152
	v_add_f32_e32 v151, v151, v153
	v_lshlrev_b32_e32 v152, 16, v84
	v_and_b32_e32 v153, 0xffff0000, v84
	v_fma_f32 v118, v150, v164, v152
	v_fma_f32 v119, v151, v165, v153
	v_lshlrev_b32_e32 v150, 16, v69
	v_and_b32_e32 v151, 0xffff0000, v69
	v_lshlrev_b32_e32 v152, 16, v77
	v_and_b32_e32 v153, 0xffff0000, v77
	v_add_f32_e32 v150, v150, v152
	v_add_f32_e32 v151, v151, v153
	v_lshlrev_b32_e32 v152, 16, v85
	v_and_b32_e32 v153, 0xffff0000, v85
	v_fma_f32 v120, v150, v164, v152
	v_fma_f32 v121, v151, v165, v153
	v_lshlrev_b32_e32 v150, 16, v70
	v_and_b32_e32 v151, 0xffff0000, v70
	v_lshlrev_b32_e32 v152, 16, v78
	v_and_b32_e32 v153, 0xffff0000, v78
	v_add_f32_e32 v150, v150, v152
	v_add_f32_e32 v151, v151, v153
	v_lshlrev_b32_e32 v152, 16, v86
	v_and_b32_e32 v153, 0xffff0000, v86
	v_fma_f32 v122, v150, v164, v152
	v_fma_f32 v123, v151, v165, v153
	v_lshlrev_b32_e32 v150, 16, v71
	v_and_b32_e32 v151, 0xffff0000, v71
	v_lshlrev_b32_e32 v152, 16, v79
	v_and_b32_e32 v153, 0xffff0000, v79
	v_add_f32_e32 v150, v150, v152
	v_add_f32_e32 v151, v151, v153
	v_lshlrev_b32_e32 v152, 16, v87
	v_and_b32_e32 v153, 0xffff0000, v87
	v_fma_f32 v124, v150, v164, v152
	v_fma_f32 v125, v151, v165, v153
	v_lshlrev_b32_e32 v150, 16, v72
	v_and_b32_e32 v151, 0xffff0000, v72
	v_lshlrev_b32_e32 v152, 16, v80
	v_and_b32_e32 v153, 0xffff0000, v80
	v_add_f32_e32 v150, v150, v152
	v_add_f32_e32 v151, v151, v153
	v_lshlrev_b32_e32 v152, 16, v88
	v_and_b32_e32 v153, 0xffff0000, v88
	v_fma_f32 v126, v150, v164, v152
	v_fma_f32 v127, v151, v165, v153
	v_lshlrev_b32_e32 v150, 16, v73
	v_and_b32_e32 v151, 0xffff0000, v73
	v_lshlrev_b32_e32 v152, 16, v81
	v_and_b32_e32 v153, 0xffff0000, v81
	v_add_f32_e32 v150, v150, v152
	v_add_f32_e32 v151, v151, v153
	v_lshlrev_b32_e32 v152, 16, v89
	v_and_b32_e32 v153, 0xffff0000, v89
	v_fma_f32 v128, v150, v164, v152
	v_fma_f32 v129, v151, v165, v153
	s_add_i32 s0, s98, 2
	s_min_u32 s0, s0, 31
	s_lshl_b32 s0, s0, 11
	s_mov_b32 s1, 0
	v_lshl_add_u64 v[184:185], s[0:1], 0, v[178:179]
	v_lshl_add_u64 v[186:187], s[0:1], 0, v[172:173]
	v_lshl_add_u64 v[188:189], s[0:1], 0, v[176:177]
	global_load_dwordx2 v[82:83], v[184:185], off offset:-1024
	global_load_dwordx2 v[84:85], v[184:185], off offset:-512
	global_load_dwordx2 v[86:87], v[184:185], off offset:0
	global_load_dwordx2 v[88:89], v[184:185], off offset:512
	global_load_dwordx2 v[66:67], v[186:187], off offset:-1024
	global_load_dwordx2 v[68:69], v[186:187], off offset:-512
	global_load_dwordx2 v[70:71], v[186:187], off offset:0
	global_load_dwordx2 v[72:73], v[186:187], off offset:512
	global_load_dwordx2 v[74:75], v[188:189], off offset:-1024
	global_load_dwordx2 v[76:77], v[188:189], off offset:-512
	global_load_dwordx2 v[78:79], v[188:189], off offset:0
	global_load_dwordx2 v[80:81], v[188:189], off offset:512
	v_add_f32_e32 v154, v114, v116
	v_add_f32_e32 v155, v115, v117
	v_add_f32_e32 v156, v118, v120
	v_add_f32_e32 v157, v119, v121
	v_add_f32_e32 v154, v154, v156
	v_add_f32_e32 v155, v155, v157
	v_add_f32_e32 v156, v122, v124
	v_add_f32_e32 v157, v123, v125
	v_add_f32_e32 v154, v154, v156
	v_add_f32_e32 v155, v155, v157
	v_add_f32_e32 v156, v126, v128
	v_add_f32_e32 v157, v127, v129
	v_add_f32_e32 v154, v154, v156
	v_add_f32_e32 v155, v155, v157
	v_add_f32_e32 v154, v154, v155
	s_nop 1
	v_add_f32_dpp v160, v154, v154 quad_perm:[1,0,3,2] row_mask:0xf bank_mask:0xf
	s_nop 1
	v_add_f32_dpp v160, v160, v160 quad_perm:[2,3,0,1] row_mask:0xf bank_mask:0xf
	s_nop 1
	v_add_f32_dpp v160, v160, v160 row_half_mirror row_mask:0xf bank_mask:0xf
	s_nop 1
	v_add_f32_dpp v160, v160, v160 row_mirror row_mask:0xf bank_mask:0xf
	s_nop 1
	v_add_f32_dpp v160, v160, v160 row_bcast:15 row_mask:0xa bank_mask:0xf
	s_nop 1
	v_add_f32_dpp v160, v160, v160 row_bcast:31 row_mask:0xc bank_mask:0xf
	s_nop 1
	v_readlane_b32 s0, v160, 63
	s_nop 2
	v_mov_b32_e32 v170, s0
	v_mul_f32_e32 v156, 0xba800000, v170
	v_mul_f32_e32 v157, 0xba800000, v170
	v_add_f32_e32 v114, v114, v156
	v_add_f32_e32 v115, v115, v157
	v_add_f32_e32 v116, v116, v156
	v_add_f32_e32 v117, v117, v157
	v_add_f32_e32 v118, v118, v156
	v_add_f32_e32 v119, v119, v157
	v_add_f32_e32 v120, v120, v156
	v_add_f32_e32 v121, v121, v157
	v_add_f32_e32 v122, v122, v156
	v_add_f32_e32 v123, v123, v157
	v_add_f32_e32 v124, v124, v156
	v_add_f32_e32 v125, v125, v157
	v_add_f32_e32 v126, v126, v156
	v_add_f32_e32 v127, v127, v157
	v_add_f32_e32 v128, v128, v156
	v_add_f32_e32 v129, v129, v157
	v_mul_f32_e32 v154, v114, v114
	v_mul_f32_e32 v155, v115, v115
	v_fma_f32 v154, v116, v116, v154
	v_fma_f32 v155, v117, v117, v155
	v_fma_f32 v154, v118, v118, v154
	v_fma_f32 v155, v119, v119, v155
	v_fma_f32 v154, v120, v120, v154
	v_fma_f32 v155, v121, v121, v155
	v_fma_f32 v154, v122, v122, v154
; __device__ __forceinline__ unsigned pk2(float lo, float hi) { return pg8::cvt_pk_bf16(lo, hi); }
; __device__ __forceinline__ float bflo(unsigned u) { return __uint_as_float(u << 16); }
; __device__ __forceinline__ float bfhi(unsigned u) { return __uint_as_float(u & 0xffff0000u); }
; __device__ __forceinline__ void ln_panel(int pm, const float* resf, const bf16* rlo, const bf16* dlt, float* xo, const float* gam, const float* bet, bf16* xb, bf16* wlo, bool fin, float alpha) {
;     ...
;         const float mean = wave_sum(s) * (1.f / DM); float s2 = 0.f;
; #pragma unroll
;         for (int j = 0; j < 4; ++j) { v[j] = v[j] - mean; s2 += (v[j].x * v[j].x + v[j].y * v[j].y) + (v[j].z * v[j].z + v[j].w * v[j].w); }
;         const float rstd = 1.f / sqrtf(wave_sum(s2) * (1.f / DM) + LN_EPS);
; #pragma unroll
;         for (int j = 0; j < 4; ++j) { const f32x4 o = v[j] * rstd * gv[j] + bv[j];
;             if (fin) *(f32x4*)(xo + grow + 256 * j) = o;
;             else { u32x2 w; w.x = pk2(o.x, o.y); w.y = pk2(o.z, o.w); *(u32x2*)(xb + grow + 256 * j) = w;
;                    u32x2 q; q.x = pk2(o.x - bflo(w.x), o.y - bfhi(w.x)); q.y = pk2(o.z - bflo(w.y), o.w - bfhi(w.y)); *(u32x2*)(wlo + prow + 256 * j) = q; } }
;     }
	v_fma_f32 v155, v123, v123, v155
	v_fma_f32 v154, v124, v124, v154
	v_fma_f32 v155, v125, v125, v155
	v_fma_f32 v154, v126, v126, v154
	v_fma_f32 v155, v127, v127, v155
	v_fma_f32 v154, v128, v128, v154
	v_fma_f32 v155, v129, v129, v155
	v_add_f32_e32 v154, v154, v155
	s_nop 1
	v_add_f32_dpp v160, v154, v154 quad_perm:[1,0,3,2] row_mask:0xf bank_mask:0xf
	s_nop 1
	v_add_f32_dpp v160, v160, v160 quad_perm:[2,3,0,1] row_mask:0xf bank_mask:0xf
	s_nop 1
	v_add_f32_dpp v160, v160, v160 row_half_mirror row_mask:0xf bank_mask:0xf
	s_nop 1
	v_add_f32_dpp v160, v160, v160 row_mirror row_mask:0xf bank_mask:0xf
	s_nop 1
	v_add_f32_dpp v160, v160, v160 row_bcast:15 row_mask:0xa bank_mask:0xf
	s_nop 1
	v_add_f32_dpp v160, v160, v160 row_bcast:31 row_mask:0xc bank_mask:0xf
	s_nop 1
	v_readlane_b32 s0, v160, 63
	s_nop 2
	v_mov_b32_e32 v170, s0
	v_fmamk_f32 v154, v170, 0x3a800000, v166
	s_mov_b32 s0, 0xf800000
	v_mul_f32_e32 v155, 0x4f800000, v154
	v_cmp_gt_f32_e32 vcc, s0, v154
	s_nop 1
	v_cndmask_b32_e32 v154, v154, v155, vcc
	v_sqrt_f32_e32 v155, v154
	s_nop 0
	v_add_u32_e32 v156, -1, v155
	v_fma_f32 v157, -v156, v155, v154
	v_cmp_ge_f32_e64 s[0:1], 0, v157
	v_add_u32_e32 v157, 1, v155
	s_nop 0
	v_cndmask_b32_e64 v156, v155, v156, s[0:1]
	v_fma_f32 v155, -v157, v155, v154
	v_cmp_lt_f32_e64 s[0:1], 0, v155
	s_nop 1
	v_cndmask_b32_e64 v155, v156, v157, s[0:1]
	v_mul_f32_e32 v156, 0x37800000, v155
	v_cndmask_b32_e32 v155, v155, v156, vcc
	v_cmp_class_f32_e32 vcc, v154, v167
	s_nop 1
	v_cndmask_b32_e32 v154, v155, v154, vcc
	v_div_scale_f32 v155, s[0:1], v154, v154, 1.0
	v_rcp_f32_e32 v156, v155
	s_nop 0
	v_fma_f32 v157, -v155, v156, 1.0
	v_fmac_f32_e32 v156, v157, v156
	v_div_scale_f32 v157, vcc, 1.0, v154, 1.0
	v_mul_f32_e32 v158, v157, v156
	v_fma_f32 v159, -v155, v158, v157
	v_fmac_f32_e32 v158, v159, v156
	v_fma_f32 v155, -v155, v158, v157
	s_nop 0
	v_div_fmas_f32 v155, v155, v156, v158
	v_div_fixup_f32 v168, v155, v154, 1.0
	s_add_i32 s0, s98, 0
	s_lshl_b32 s0, s0, 11
	s_mov_b32 s1, 0
	v_lshl_add_u64 v[184:185], s[0:1], 1, v[182:183]
	v_mul_f32_e32 v190, v114, v168
	v_mul_f32_e32 v191, v115, v168
	v_fma_f32 v190, v0, v190, v8
	v_fma_f32 v191, v1, v191, v9
	v_mul_f32_e32 v192, v116, v168
	v_mul_f32_e32 v193, v117, v168
	v_fma_f32 v192, v2, v192, v10
	v_fma_f32 v193, v3, v193, v11
	v_mul_f32_e32 v194, v118, v168
	v_mul_f32_e32 v195, v119, v168
	v_fma_f32 v194, v4, v194, v12
	v_fma_f32 v195, v5, v195, v13
	v_mul_f32_e32 v196, v120, v168
	v_mul_f32_e32 v197, v121, v168
	v_fma_f32 v196, v6, v196, v14
	v_fma_f32 v197, v7, v197, v15
	v_mul_f32_e32 v198, v122, v168
	v_mul_f32_e32 v199, v123, v168
	v_fma_f32 v198, v16, v198, v24
	v_fma_f32 v199, v17, v199, v25
	v_mul_f32_e32 v200, v124, v168
	v_mul_f32_e32 v201, v125, v168
	v_fma_f32 v200, v18, v200, v26
	v_fma_f32 v201, v19, v201, v27
	v_mul_f32_e32 v202, v126, v168
	v_mul_f32_e32 v203, v127, v168
	v_fma_f32 v202, v20, v202, v28
	v_fma_f32 v203, v21, v203, v29
	v_mul_f32_e32 v204, v128, v168
	v_mul_f32_e32 v205, v129, v168
	v_fma_f32 v204, v22, v204, v30
	v_fma_f32 v205, v23, v205, v31
	global_store_dwordx4 v[184:185], v[190:193], off offset:-2048
	global_store_dwordx4 v[184:185], v[194:197], off offset:-1024
	global_store_dwordx4 v[184:185], v[198:201], off offset:0
	global_store_dwordx4 v[184:185], v[202:205], off offset:1024
	s_waitcnt vmcnt(16)
	v_lshlrev_b32_e32 v150, 16, v90
	v_and_b32_e32 v151, 0xffff0000, v90
	v_lshlrev_b32_e32 v152, 16, v98
	v_and_b32_e32 v153, 0xffff0000, v98
	v_add_f32_e32 v150, v150, v152
	v_add_f32_e32 v151, v151, v153
	v_lshlrev_b32_e32 v152, 16, v106
	v_and_b32_e32 v153, 0xffff0000, v106
	v_fma_f32 v114, v150, v164, v152
	v_fma_f32 v115, v151, v165, v153
	v_lshlrev_b32_e32 v150, 16, v91
	v_and_b32_e32 v151, 0xffff0000, v91
	v_lshlrev_b32_e32 v152, 16, v99
	v_and_b32_e32 v153, 0xffff0000, v99
	v_add_f32_e32 v150, v150, v152
	v_add_f32_e32 v151, v151, v153
	v_lshlrev_b32_e32 v152, 16, v107
	v_and_b32_e32 v153, 0xffff0000, v107
	v_fma_f32 v116, v150, v164, v152
	v_fma_f32 v117, v151, v165, v153
	v_lshlrev_b32_e32 v150, 16, v92
	v_and_b32_e32 v151, 0xffff0000, v92
	v_lshlrev_b32_e32 v152, 16, v100
	v_and_b32_e32 v153, 0xffff0000, v100
	v_add_f32_e32 v150, v150, v152
	v_add_f32_e32 v151, v151, v153
	v_lshlrev_b32_e32 v152, 16, v108
	v_and_b32_e32 v153, 0xffff0000, v108
	v_fma_f32 v118, v150, v164, v152
	v_fma_f32 v119, v151, v165, v153
	v_lshlrev_b32_e32 v150, 16, v93
	v_and_b32_e32 v151, 0xffff0000, v93
	v_lshlrev_b32_e32 v152, 16, v101
	v_and_b32_e32 v153, 0xffff0000, v101
	v_add_f32_e32 v150, v150, v152
	v_add_f32_e32 v151, v151, v153
	v_lshlrev_b32_e32 v152, 16, v109
	v_and_b32_e32 v153, 0xffff0000, v109
	v_fma_f32 v120, v150, v164, v152
	v_fma_f32 v121, v151, v165, v153
	v_lshlrev_b32_e32 v150, 16, v94
	v_and_b32_e32 v151, 0xffff0000, v94
	v_lshlrev_b32_e32 v152, 16, v102
	v_and_b32_e32 v153, 0xffff0000, v102
	v_add_f32_e32 v150, v150, v152
	v_add_f32_e32 v151, v151, v153
	v_lshlrev_b32_e32 v152, 16, v110
	v_and_b32_e32 v153, 0xffff0000, v110
	v_fma_f32 v122, v150, v164, v152
	v_fma_f32 v123, v151, v165, v153
	v_lshlrev_b32_e32 v150, 16, v95
	v_and_b32_e32 v151, 0xffff0000, v95
	v_lshlrev_b32_e32 v152, 16, v103
	v_and_b32_e32 v153, 0xffff0000, v103
	v_add_f32_e32 v150, v150, v152
	v_add_f32_e32 v151, v151, v153
	v_lshlrev_b32_e32 v152, 16, v111
	v_and_b32_e32 v153, 0xffff0000, v111
	v_fma_f32 v124, v150, v164, v152
	v_fma_f32 v125, v151, v165, v153
	v_lshlrev_b32_e32 v150, 16, v96
	v_and_b32_e32 v151, 0xffff0000, v96
	v_lshlrev_b32_e32 v152, 16, v104
	v_and_b32_e32 v153, 0xffff0000, v104
	v_add_f32_e32 v150, v150, v152
	v_add_f32_e32 v151, v151, v153
	v_lshlrev_b32_e32 v152, 16, v112
; __device__ __forceinline__ unsigned pk2(float lo, float hi) { return pg8::cvt_pk_bf16(lo, hi); }
; __device__ __forceinline__ float bflo(unsigned u) { return __uint_as_float(u << 16); }
; __device__ __forceinline__ float bfhi(unsigned u) { return __uint_as_float(u & 0xffff0000u); }
; __device__ __forceinline__ void ln_panel(int pm, const float* resf, const bf16* rlo, const bf16* dlt, float* xo, const float* gam, const float* bet, bf16* xb, bf16* wlo, bool fin, float alpha) {
;     ...
;         for (int j = 0; j < 4; ++j) { f32x4 x; const u32x2 d = *(const u32x2*)(dlt + prow + 256 * j);
;             if (resf) x = *(const f32x4*)(resf + grow + 256 * j);
;             else { const u32x2 h = *(const u32x2*)(xb + grow + 256 * j), l = *(const u32x2*)(rlo + prow + 256 * j);
;                    x = (f32x4){bflo(h.x) + bflo(l.x), bfhi(h.x) + bfhi(l.x), bflo(h.y) + bflo(l.y), bfhi(h.y) + bfhi(l.y)}; }
;             v[j] = (f32x4){x.x * alpha + bflo(d.x), x.y * alpha + bfhi(d.x), x.z * alpha + bflo(d.y), x.w * alpha + bfhi(d.y)}; s += (v[j].x + v[j].y) + (v[j].z + v[j].w); }
;         const float mean = wave_sum(s) * (1.f / DM); float s2 = 0.f;
; #pragma unroll
;         for (int j = 0; j < 4; ++j) { v[j] = v[j] - mean; s2 += (v[j].x * v[j].x + v[j].y * v[j].y) + (v[j].z * v[j].z + v[j].w * v[j].w); }
;         const float rstd = 1.f / sqrtf(wave_sum(s2) * (1.f / DM) + LN_EPS);
; #pragma unroll
;         for (int j = 0; j < 4; ++j) { const f32x4 o = v[j] * rstd * gv[j] + bv[j];
;             if (fin) *(f32x4*)(xo + grow + 256 * j) = o;
;             else { u32x2 w; w.x = pk2(o.x, o.y); w.y = pk2(o.z, o.w); *(u32x2*)(xb + grow + 256 * j) = w;
;                    u32x2 q; q.x = pk2(o.x - bflo(w.x), o.y - bfhi(w.x)); q.y = pk2(o.z - bflo(w.y), o.w - bfhi(w.y)); *(u32x2*)(wlo + prow + 256 * j) = q; } }
;     }
	v_and_b32_e32 v153, 0xffff0000, v112
	v_fma_f32 v126, v150, v164, v152
	v_fma_f32 v127, v151, v165, v153
	v_lshlrev_b32_e32 v150, 16, v97
	v_and_b32_e32 v151, 0xffff0000, v97
	v_lshlrev_b32_e32 v152, 16, v105
	v_and_b32_e32 v153, 0xffff0000, v105
	v_add_f32_e32 v150, v150, v152
	v_add_f32_e32 v151, v151, v153
	v_lshlrev_b32_e32 v152, 16, v113
	v_and_b32_e32 v153, 0xffff0000, v113
	v_fma_f32 v128, v150, v164, v152
	v_fma_f32 v129, v151, v165, v153
	s_add_i32 s0, s98, 3
	s_min_u32 s0, s0, 31
	s_lshl_b32 s0, s0, 11
	s_mov_b32 s1, 0
	v_lshl_add_u64 v[184:185], s[0:1], 0, v[178:179]
	v_lshl_add_u64 v[186:187], s[0:1], 0, v[172:173]
	v_lshl_add_u64 v[188:189], s[0:1], 0, v[176:177]
	global_load_dwordx2 v[106:107], v[184:185], off offset:-1024
	global_load_dwordx2 v[108:109], v[184:185], off offset:-512
	global_load_dwordx2 v[110:111], v[184:185], off offset:0
	global_load_dwordx2 v[112:113], v[184:185], off offset:512
	global_load_dwordx2 v[90:91], v[186:187], off offset:-1024
	global_load_dwordx2 v[92:93], v[186:187], off offset:-512
	global_load_dwordx2 v[94:95], v[186:187], off offset:0
	global_load_dwordx2 v[96:97], v[186:187], off offset:512
	global_load_dwordx2 v[98:99], v[188:189], off offset:-1024
	global_load_dwordx2 v[100:101], v[188:189], off offset:-512
	global_load_dwordx2 v[102:103], v[188:189], off offset:0
	global_load_dwordx2 v[104:105], v[188:189], off offset:512
	v_add_f32_e32 v154, v114, v116
	v_add_f32_e32 v155, v115, v117
	v_add_f32_e32 v156, v118, v120
	v_add_f32_e32 v157, v119, v121
	v_add_f32_e32 v154, v154, v156
	v_add_f32_e32 v155, v155, v157
	v_add_f32_e32 v156, v122, v124
	v_add_f32_e32 v157, v123, v125
	v_add_f32_e32 v154, v154, v156
	v_add_f32_e32 v155, v155, v157
	v_add_f32_e32 v156, v126, v128
	v_add_f32_e32 v157, v127, v129
	v_add_f32_e32 v154, v154, v156
	v_add_f32_e32 v155, v155, v157
	v_add_f32_e32 v154, v154, v155
	s_nop 1
	v_add_f32_dpp v160, v154, v154 quad_perm:[1,0,3,2] row_mask:0xf bank_mask:0xf
	s_nop 1
	v_add_f32_dpp v160, v160, v160 quad_perm:[2,3,0,1] row_mask:0xf bank_mask:0xf
	s_nop 1
	v_add_f32_dpp v160, v160, v160 row_half_mirror row_mask:0xf bank_mask:0xf
	s_nop 1
	v_add_f32_dpp v160, v160, v160 row_mirror row_mask:0xf bank_mask:0xf
	s_nop 1
	v_add_f32_dpp v160, v160, v160 row_bcast:15 row_mask:0xa bank_mask:0xf
	s_nop 1
	v_add_f32_dpp v160, v160, v160 row_bcast:31 row_mask:0xc bank_mask:0xf
	s_nop 1
	v_readlane_b32 s0, v160, 63
	s_nop 2
	v_mov_b32_e32 v170, s0
	v_mul_f32_e32 v156, 0xba800000, v170
	v_mul_f32_e32 v157, 0xba800000, v170
	v_add_f32_e32 v114, v114, v156
	v_add_f32_e32 v115, v115, v157
	v_add_f32_e32 v116, v116, v156
	v_add_f32_e32 v117, v117, v157
	v_add_f32_e32 v118, v118, v156
	v_add_f32_e32 v119, v119, v157
	v_add_f32_e32 v120, v120, v156
	v_add_f32_e32 v121, v121, v157
	v_add_f32_e32 v122, v122, v156
	v_add_f32_e32 v123, v123, v157
	v_add_f32_e32 v124, v124, v156
	v_add_f32_e32 v125, v125, v157
	v_add_f32_e32 v126, v126, v156
	v_add_f32_e32 v127, v127, v157
	v_add_f32_e32 v128, v128, v156
	v_add_f32_e32 v129, v129, v157
	v_mul_f32_e32 v154, v114, v114
	v_mul_f32_e32 v155, v115, v115
	v_fma_f32 v154, v116, v116, v154
	v_fma_f32 v155, v117, v117, v155
	v_fma_f32 v154, v118, v118, v154
	v_fma_f32 v155, v119, v119, v155
	v_fma_f32 v154, v120, v120, v154
	v_fma_f32 v155, v121, v121, v155
	v_fma_f32 v154, v122, v122, v154
	v_fma_f32 v155, v123, v123, v155
	v_fma_f32 v154, v124, v124, v154
	v_fma_f32 v155, v125, v125, v155
	v_fma_f32 v154, v126, v126, v154
	v_fma_f32 v155, v127, v127, v155
	v_fma_f32 v154, v128, v128, v154
	v_fma_f32 v155, v129, v129, v155
	v_add_f32_e32 v154, v154, v155
	s_nop 1
	v_add_f32_dpp v160, v154, v154 quad_perm:[1,0,3,2] row_mask:0xf bank_mask:0xf
	s_nop 1
	v_add_f32_dpp v160, v160, v160 quad_perm:[2,3,0,1] row_mask:0xf bank_mask:0xf
	s_nop 1
	v_add_f32_dpp v160, v160, v160 row_half_mirror row_mask:0xf bank_mask:0xf
	s_nop 1
	v_add_f32_dpp v160, v160, v160 row_mirror row_mask:0xf bank_mask:0xf
	s_nop 1
	v_add_f32_dpp v160, v160, v160 row_bcast:15 row_mask:0xa bank_mask:0xf
	s_nop 1
	v_add_f32_dpp v160, v160, v160 row_bcast:31 row_mask:0xc bank_mask:0xf
	s_nop 1
	v_readlane_b32 s0, v160, 63
	s_nop 2
	v_mov_b32_e32 v170, s0
	v_fmamk_f32 v154, v170, 0x3a800000, v166
	s_mov_b32 s0, 0xf800000
	v_mul_f32_e32 v155, 0x4f800000, v154
	v_cmp_gt_f32_e32 vcc, s0, v154
	s_nop 1
	v_cndmask_b32_e32 v154, v154, v155, vcc
	v_sqrt_f32_e32 v155, v154
	s_nop 0
	v_add_u32_e32 v156, -1, v155
	v_fma_f32 v157, -v156, v155, v154
	v_cmp_ge_f32_e64 s[0:1], 0, v157
	v_add_u32_e32 v157, 1, v155
	s_nop 0
	v_cndmask_b32_e64 v156, v155, v156, s[0:1]
	v_fma_f32 v155, -v157, v155, v154
	v_cmp_lt_f32_e64 s[0:1], 0, v155
	s_nop 1
	v_cndmask_b32_e64 v155, v156, v157, s[0:1]
	v_mul_f32_e32 v156, 0x37800000, v155
	v_cndmask_b32_e32 v155, v155, v156, vcc
	v_cmp_class_f32_e32 vcc, v154, v167
	s_nop 1
	v_cndmask_b32_e32 v154, v155, v154, vcc
	v_div_scale_f32 v155, s[0:1], v154, v154, 1.0
	v_rcp_f32_e32 v156, v155
	s_nop 0
	v_fma_f32 v157, -v155, v156, 1.0
	v_fmac_f32_e32 v156, v157, v156
	v_div_scale_f32 v157, vcc, 1.0, v154, 1.0
	v_mul_f32_e32 v158, v157, v156
	v_fma_f32 v159, -v155, v158, v157
	v_fmac_f32_e32 v158, v159, v156
	v_fma_f32 v155, -v155, v158, v157
	s_nop 0
	v_div_fmas_f32 v155, v155, v156, v158
	v_div_fixup_f32 v168, v155, v154, 1.0
	s_add_i32 s0, s98, 1
	s_lshl_b32 s0, s0, 11
	s_mov_b32 s1, 0
	v_lshl_add_u64 v[184:185], s[0:1], 1, v[182:183]
	v_mul_f32_e32 v190, v114, v168
	v_mul_f32_e32 v191, v115, v168
	v_fma_f32 v190, v0, v190, v8
	v_fma_f32 v191, v1, v191, v9
	v_mul_f32_e32 v192, v116, v168
	v_mul_f32_e32 v193, v117, v168
	v_fma_f32 v192, v2, v192, v10
	v_fma_f32 v193, v3, v193, v11
	v_mul_f32_e32 v194, v118, v168
	v_mul_f32_e32 v195, v119, v168
	v_fma_f32 v194, v4, v194, v12
	v_fma_f32 v195, v5, v195, v13
	v_mul_f32_e32 v196, v120, v168
	v_mul_f32_e32 v197, v121, v168
	v_fma_f32 v196, v6, v196, v14
	v_fma_f32 v197, v7, v197, v15
	v_mul_f32_e32 v198, v122, v168
	v_mul_f32_e32 v199, v123, v168
	v_fma_f32 v198, v16, v198, v24
	v_fma_f32 v199, v17, v199, v25
	v_mul_f32_e32 v200, v124, v168
	v_mul_f32_e32 v201, v125, v168
	v_fma_f32 v200, v18, v200, v26
	v_fma_f32 v201, v19, v201, v27
	v_mul_f32_e32 v202, v126, v168
	v_mul_f32_e32 v203, v127, v168
	v_fma_f32 v202, v20, v202, v28
	v_fma_f32 v203, v21, v203, v29
	v_mul_f32_e32 v204, v128, v168
	v_mul_f32_e32 v205, v129, v168
	v_fma_f32 v204, v22, v204, v30
	v_fma_f32 v205, v23, v205, v31
	global_store_dwordx4 v[184:185], v[190:193], off offset:-2048
	global_store_dwordx4 v[184:185], v[194:197], off offset:-1024
	global_store_dwordx4 v[184:185], v[198:201], off offset:0
	global_store_dwordx4 v[184:185], v[202:205], off offset:1024
	s_add_i32 s98, s98, 2
	s_cmp_lt_u32 s98, 32
	s_cbranch_scc1 .Lmy_ln2f_loop
	s_waitcnt vmcnt(0)
	s_branch .LBB0_467
